# mixer chunks made team-local and P7 output moved to slab 4 so seam 5 is also a team barrier; static barrier targets; 11 team + 2 grid barriers
# speedup vs baseline: 1.0403x; 1.0032x over previous
; __device__ __forceinline__ unsigned xb_ld(unsigned* p)              { return __hip_atomic_load(p, __ATOMIC_RELAXED, __HIP_MEMORY_SCOPE_AGENT); }
; __device__ __forceinline__ unsigned xb_add(unsigned* p, unsigned v) { return __hip_atomic_fetch_add(p, v, __ATOMIC_RELAXED, __HIP_MEMORY_SCOPE_AGENT); }
; #define XB_SPIN(cond, bar) do { unsigned _sp = 0; while (cond) { __builtin_amdgcn_s_sleep(1); \
;     if ((++_sp & 255u) == 0u) { if (xb_ld(&(bar)[XB_TMO])) break; if (_sp > XB_SPIN_CAP) { atomicAdd(&(bar)[XB_TMO], 1u); break; } } } } while (0)
; __device__ __forceinline__ void xcd_barrier(const XcdBarrier& b) {
;     asm volatile("s_waitcnt vmcnt(0)" ::: "memory");
;     __syncthreads();
;     if (threadIdx.x == 0) {
;         unsigned* bar = b.bar;
;         __builtin_amdgcn_s_waitcnt(0);
;         unsigned nloc = b.st[0], nx = b.st[1];
;         if (nloc == 0u) { xcd_barrier_complete(bar, b.x, nloc, nx); b.st[0] = nloc; b.st[1] = nx; }
;         const unsigned old = xb_add(&bar[XB_XSUB(b.x)], 1u);
;         const unsigned gen = old / nloc;
;         if (old + 1u == (gen + 1u) * nloc) {
;             __builtin_amdgcn_fence(__ATOMIC_RELEASE, "agent");
;             asm volatile("s_waitcnt vmcnt(0)" ::: "memory");
;             const unsigned og = xb_add(&bar[XB_TOP], 1u);
;             const unsigned tg = og / nx;
;             if (og + 1u == (tg + 1u) * nx) xb_add(&bar[XB_TOPGEN], 1u);
;             else XB_SPIN(xb_ld(&bar[XB_TOPGEN]) == tg, bar);
;             __builtin_amdgcn_fence(__ATOMIC_ACQUIRE, "agent");
;             xb_add(&bar[XB_XGEN(b.x)], 1u);
;             asm volatile("s_waitcnt vmcnt(0)" ::: "memory");
;         } else {
;             XB_SPIN(xb_ld(&bar[XB_XGEN(b.x)]) == gen, bar);
;             __builtin_amdgcn_fence(__ATOMIC_ACQUIRE, "agent");
;             asm volatile("s_waitcnt vmcnt(0)" ::: "memory");
;         }
.LBB0_257:
	s_cmp_gt_i32 s31, 2
	s_cselect_b64 s[0:1], -1, 0
	s_and_b64 s[4:5], s[12:13], s[0:1]
	s_andn2_b64 vcc, exec, s[4:5]
	s_cbranch_vccnz .LBB0_307
	s_waitcnt vmcnt(0)
	s_barrier
	v_cmp_eq_u32_e32 vcc, 0, v195
	s_and_saveexec_b64 s[4:5], vcc
	s_cbranch_execz .Ltb307_done
	s_and_b32 s3, s2, 7
	s_lshl_b32 s3, s3, 3
	s_bfe_u32 s13, s2, 0x30003
	s_or_b32 s3, s3, s13
	s_lshl_b32 s3, s3, 5
	s_add_u32 s8, s28, 0x3903600
	s_addc_u32 s9, s29, 0
	v_mov_b32_e32 v0, s3
	v_mov_b32_e32 v1, 1
	v_mov_b32_e32 v2, 4
	s_mov_b32 s15, 0
	s_cmp_eq_u32 s99, 1
	s_cbranch_scc1 .Ltb307_fast
	buffer_wbl2 sc1
	s_waitcnt vmcnt(0)
	global_atomic_add v0, v1, s[8:9]

; __device__ __forceinline__ unsigned xb_ld(unsigned* p)              { return __hip_atomic_load(p, __ATOMIC_RELAXED, __HIP_MEMORY_SCOPE_AGENT); }
; __device__ __forceinline__ unsigned xb_add(unsigned* p, unsigned v) { return __hip_atomic_fetch_add(p, v, __ATOMIC_RELAXED, __HIP_MEMORY_SCOPE_AGENT); }
; #define XB_SPIN(cond, bar) do { unsigned _sp = 0; while (cond) { __builtin_amdgcn_s_sleep(1); \
;     if ((++_sp & 255u) == 0u) { if (xb_ld(&(bar)[XB_TMO])) break; if (_sp > XB_SPIN_CAP) { atomicAdd(&(bar)[XB_TMO], 1u); break; } } } } while (0)
; __device__ __forceinline__ void xcd_barrier(const XcdBarrier& b) {
;     ...
;             const unsigned og = xb_add(&bar[XB_TOP], 1u);
;             const unsigned tg = og / nx;
;             if (og + 1u == (tg + 1u) * nx) xb_add(&bar[XB_TOPGEN], 1u);
;             else XB_SPIN(xb_ld(&bar[XB_TOPGEN]) == tg, bar);
;             __builtin_amdgcn_fence(__ATOMIC_ACQUIRE, "agent");
;             xb_add(&bar[XB_XGEN(b.x)], 1u);
;             asm volatile("s_waitcnt vmcnt(0)" ::: "memory");
;         } else {
;             XB_SPIN(xb_ld(&bar[XB_XGEN(b.x)]) == gen, bar);
;             __builtin_amdgcn_fence(__ATOMIC_ACQUIRE, "agent");
;             asm volatile("s_waitcnt vmcnt(0)" ::: "memory");
;         }
.Ltb307_srel:
	buffer_inv sc1
	s_waitcnt vmcnt(0)
	s_branch .Ltb307_done
.Ltb307_fast:
	global_atomic_add v0, v1, s[8:9]
	buffer_inv sc1
.Ltb307_spin:
	global_load_dword v3, v0, s[8:9] sc1
	s_waitcnt vmcnt(0)
	v_cmp_ge_u32_e32 vcc, v3, v2
	s_cbranch_vccnz .Ltb307_done
	s_add_u32 s15, s15, 1
	s_cmp_lt_u32 s15, 0x400000
	s_cbranch_scc1 .Ltb307_spin

; __device__ __forceinline__ unsigned xb_ld(unsigned* p)              { return __hip_atomic_load(p, __ATOMIC_RELAXED, __HIP_MEMORY_SCOPE_AGENT); }
; __device__ __forceinline__ unsigned xb_add(unsigned* p, unsigned v) { return __hip_atomic_fetch_add(p, v, __ATOMIC_RELAXED, __HIP_MEMORY_SCOPE_AGENT); }
; #define XB_SPIN(cond, bar) do { unsigned _sp = 0; while (cond) { __builtin_amdgcn_s_sleep(1); \
;     if ((++_sp & 255u) == 0u) { if (xb_ld(&(bar)[XB_TMO])) break; if (_sp > XB_SPIN_CAP) { atomicAdd(&(bar)[XB_TMO], 1u); break; } } } } while (0)
; __device__ __forceinline__ void xcd_barrier(const XcdBarrier& b) {
;     asm volatile("s_waitcnt vmcnt(0)" ::: "memory");
;     __syncthreads();
;     if (threadIdx.x == 0) {
;         unsigned* bar = b.bar;
;         __builtin_amdgcn_s_waitcnt(0);
;         unsigned nloc = b.st[0], nx = b.st[1];
;         if (nloc == 0u) { xcd_barrier_complete(bar, b.x, nloc, nx); b.st[0] = nloc; b.st[1] = nx; }
;         const unsigned old = xb_add(&bar[XB_XSUB(b.x)], 1u);
;         const unsigned gen = old / nloc;
;         if (old + 1u == (gen + 1u) * nloc) {
;             __builtin_amdgcn_fence(__ATOMIC_RELEASE, "agent");
;             asm volatile("s_waitcnt vmcnt(0)" ::: "memory");
;             const unsigned og = xb_add(&bar[XB_TOP], 1u);
;             const unsigned tg = og / nx;
;             if (og + 1u == (tg + 1u) * nx) xb_add(&bar[XB_TOPGEN], 1u);
;             else XB_SPIN(xb_ld(&bar[XB_TOPGEN]) == tg, bar);
;             __builtin_amdgcn_fence(__ATOMIC_ACQUIRE, "agent");
;             xb_add(&bar[XB_XGEN(b.x)], 1u);
;             asm volatile("s_waitcnt vmcnt(0)" ::: "memory");
;         } else {
;             XB_SPIN(xb_ld(&bar[XB_XGEN(b.x)]) == gen, bar);
;             __builtin_amdgcn_fence(__ATOMIC_ACQUIRE, "agent");
;             asm volatile("s_waitcnt vmcnt(0)" ::: "memory");
;         }
.LBB0_336:
	s_cmp_gt_i32 s31, 3
	s_cselect_b64 s[0:1], -1, 0
	s_and_b64 s[4:5], s[12:13], s[0:1]
	s_andn2_b64 vcc, exec, s[4:5]
	s_cbranch_vccnz .LBB0_386
	s_waitcnt vmcnt(0)
	s_barrier
	v_cmp_eq_u32_e32 vcc, 0, v195
	s_and_saveexec_b64 s[4:5], vcc
	s_cbranch_execz .Ltb386_done
	s_and_b32 s3, s2, 7
	s_lshl_b32 s3, s3, 3
	s_bfe_u32 s13, s2, 0x30003
	s_or_b32 s3, s3, s13
	s_lshl_b32 s3, s3, 5
	s_add_u32 s8, s28, 0x3903600
	s_addc_u32 s9, s29, 0
	v_mov_b32_e32 v0, s3
	v_mov_b32_e32 v1, 1
	v_mov_b32_e32 v2, 8
	s_mov_b32 s15, 0
	s_cmp_eq_u32 s99, 1
	s_cbranch_scc1 .Ltb386_fast
	buffer_wbl2 sc1
	s_waitcnt vmcnt(0)
	global_atomic_add v0, v1, s[8:9]

; __device__ __forceinline__ unsigned xb_ld(unsigned* p)              { return __hip_atomic_load(p, __ATOMIC_RELAXED, __HIP_MEMORY_SCOPE_AGENT); }
; __device__ __forceinline__ unsigned xb_add(unsigned* p, unsigned v) { return __hip_atomic_fetch_add(p, v, __ATOMIC_RELAXED, __HIP_MEMORY_SCOPE_AGENT); }
; #define XB_SPIN(cond, bar) do { unsigned _sp = 0; while (cond) { __builtin_amdgcn_s_sleep(1); \
;     if ((++_sp & 255u) == 0u) { if (xb_ld(&(bar)[XB_TMO])) break; if (_sp > XB_SPIN_CAP) { atomicAdd(&(bar)[XB_TMO], 1u); break; } } } } while (0)
; __device__ __forceinline__ void xcd_barrier(const XcdBarrier& b) {
;     asm volatile("s_waitcnt vmcnt(0)" ::: "memory");
;     __syncthreads();
;     if (threadIdx.x == 0) {
;         unsigned* bar = b.bar;
;         __builtin_amdgcn_s_waitcnt(0);
;         unsigned nloc = b.st[0], nx = b.st[1];
;         if (nloc == 0u) { xcd_barrier_complete(bar, b.x, nloc, nx); b.st[0] = nloc; b.st[1] = nx; }
;         const unsigned old = xb_add(&bar[XB_XSUB(b.x)], 1u);
;         const unsigned gen = old / nloc;
;         if (old + 1u == (gen + 1u) * nloc) {
;             __builtin_amdgcn_fence(__ATOMIC_RELEASE, "agent");
;             asm volatile("s_waitcnt vmcnt(0)" ::: "memory");
;             const unsigned og = xb_add(&bar[XB_TOP], 1u);
;             const unsigned tg = og / nx;
;             if (og + 1u == (tg + 1u) * nx) xb_add(&bar[XB_TOPGEN], 1u);
;             else XB_SPIN(xb_ld(&bar[XB_TOPGEN]) == tg, bar);
;             __builtin_amdgcn_fence(__ATOMIC_ACQUIRE, "agent");
;             xb_add(&bar[XB_XGEN(b.x)], 1u);
;             asm volatile("s_waitcnt vmcnt(0)" ::: "memory");
;         } else {
;             XB_SPIN(xb_ld(&bar[XB_XGEN(b.x)]) == gen, bar);
;             __builtin_amdgcn_fence(__ATOMIC_ACQUIRE, "agent");
;             asm volatile("s_waitcnt vmcnt(0)" ::: "memory");
;         }
.LBB0_432:
	s_cmp_gt_i32 s31, 4
	s_cselect_b64 s[0:1], -1, 0
	s_and_b64 s[4:5], s[12:13], s[0:1]
	s_andn2_b64 vcc, exec, s[4:5]
	s_cbranch_vccnz .LBB0_482
	s_waitcnt vmcnt(0)
	s_barrier
	v_cmp_eq_u32_e32 vcc, 0, v195
	s_and_saveexec_b64 s[4:5], vcc
	s_cbranch_execz .Ltb482_done
	s_and_b32 s3, s2, 7
	s_lshl_b32 s3, s3, 3
	s_bfe_u32 s13, s2, 0x30003
	s_or_b32 s3, s3, s13
	s_lshl_b32 s3, s3, 5
	s_add_u32 s8, s28, 0x3903600
	s_addc_u32 s9, s29, 0
	v_mov_b32_e32 v0, s3
	v_mov_b32_e32 v1, 1
	v_mov_b32_e32 v2, 12
	s_mov_b32 s15, 0
	s_cmp_eq_u32 s99, 1
	s_cbranch_scc1 .Ltb482_fast
	buffer_wbl2 sc1
	s_waitcnt vmcnt(0)
	global_atomic_add v0, v1, s[8:9]

; #define LAS __attribute__((address_space(3)))
; __device__ __forceinline__ void mixer_phase(LAS unsigned char* lds, bf16* U  , const bf16* V, const bf16* C, bf16* Bout,
;                                             const bf16* wsb, const float* sgu_b, const float* sgu_g, const bf16* pwT, const float* pool_scale, int G, int bid) {
;     const int tid = threadIdx.x, wid = __builtin_amdgcn_readfirstlane(tid >> 6), lane = tid & 63, fr = lane & 15, fq = lane >> 4;
;     LAS float* stat = (LAS float*)(lds + MX_STAT_OFF);
;     for (int q = bid; q < M / 128; q += G) {
;         const int r0 = q * 128;
; #pragma unroll 1
;         for (int ib = 0; ib < 16; ib += 4) {
;             v4u raw[4][2];
; #pragma unroll
;             for (int i = 0; i < 4; ++i) { const v4u* vr = (const v4u*)(V + (size_t)(r0 + wid * 16 + ib + i) * D); raw[i][0] = vr[lane]; raw[i][1] = vr[lane + 64]; }
.LBB0_675:
	s_mov_b32 s98, s2
	s_and_b32 s101, s2, 7
	s_lshl_b32 s101, s101, 4
	s_bfe_u32 s2, s98, 0x30003
	s_add_u32 s101, s101, s2
	s_lshr_b32 s2, s98, 7
	s_lshl_b32 s2, s2, 3
	s_add_u32 s101, s101, s2
	s_lshl_b32 s101, s101, 1
	s_bfe_u32 s2, s98, 0x10006
	s_add_u32 s2, s101, s2
	s_cmp_lt_i32 s30, 6
	s_cselect_b64 s[4:5], -1, 0
	s_add_u32 s26, s28, 0xd000000
	s_addc_u32 s27, s29, 0
	s_add_u32 s22, s28, 0x11000000
	s_addc_u32 s23, s29, 0
	s_and_b64 s[14:15], s[4:5], s[0:1]
	s_andn2_b64 vcc, exec, s[14:15]
	s_cbranch_vccnz .LBB0_719
	s_cmpk_gt_i32 s2, 0xff
	v_readfirstlane_b32 s6, v195
	s_cbranch_scc1 .LBB0_719
	s_waitcnt vmcnt(0)
	v_mbcnt_lo_u32_b32 v0, -1, 0
	v_mbcnt_hi_u32_b32 v0, -1, v0
	v_and_b32_e32 v1, 64, v0
	v_add_u32_e32 v1, 64, v1
	v_xor_b32_e32 v2, 1, v0
	v_cmp_lt_i32_e32 vcc, v2, v1
	v_lshlrev_b32_e32 v4, 4, v195
	v_and_b32_e32 v104, 0xf0, v4
	v_cndmask_b32_e32 v2, v0, v2, vcc
	v_lshlrev_b32_e32 v119, 2, v2
	v_xor_b32_e32 v2, 2, v0
	v_cmp_lt_i32_e32 vcc, v2, v1
	v_mov_b32_e32 v105, 0
	v_lshlrev_b32_e32 v5, 3, v195
	v_cndmask_b32_e32 v2, v0, v2, vcc
	v_lshlrev_b32_e32 v121, 2, v2
	v_xor_b32_e32 v2, 4, v0
	v_cmp_lt_i32_e32 vcc, v2, v1
	s_mov_b64 s[4:5], 0x3600000
	v_mov_b32_e32 v3, v105
	v_cndmask_b32_e32 v2, v0, v2, vcc
	v_lshlrev_b32_e32 v123, 2, v2
	v_xor_b32_e32 v2, 8, v0
	v_cmp_lt_i32_e32 vcc, v2, v1
	s_lshr_b32 s3, s6, 6
	s_lshl_b32 s12, s3, 4
	v_cndmask_b32_e32 v2, v0, v2, vcc
	v_lshlrev_b32_e32 v129, 2, v2
	v_xor_b32_e32 v2, 16, v0
	v_cmp_lt_i32_e32 vcc, v2, v1
	s_lshl_b32 s13, s3, 5
	s_andn2_b32 s6, s6, 63
	v_cndmask_b32_e32 v2, v0, v2, vcc
	v_lshlrev_b32_e32 v131, 2, v2
	v_xor_b32_e32 v2, 32, v0
	v_cmp_lt_i32_e32 vcc, v2, v1
	s_add_u32 s6, s16, s6
	v_lshlrev_b32_e32 v7, 1, v195
	v_cndmask_b32_e32 v0, v0, v2, vcc
	v_lshlrev_b32_e32 v133, 2, v0
	v_lshl_add_u64 v[0:1], s[28:29], 0, v[104:105]
	v_lshl_add_u64 v[106:107], v[0:1], 0, s[4:5]
	v_and_b32_e32 v0, 0xf8, v5
	v_lshlrev_b32_e32 v2, 1, v0
	v_lshl_add_u64 v[110:111], s[26:27], 0, v[2:3]
	v_lshlrev_b32_e32 v2, 2, v0
	v_lshl_add_u64 v[112:113], s[38:39], 0, v[2:3]
	v_and_b32_e32 v2, 0x100, v195
	v_cmp_eq_u32_e64 s[4:5], 0, v2
	v_lshrrev_b32_e32 v2, 1, v195
	v_and_b32_e32 v6, 24, v2
	v_add_u32_e32 v1, 0, v104
	s_addc_u32 s7, s17, 0
	v_lshlrev_b32_e32 v104, 1, v6
	v_and_b32_e32 v8, 24, v7
	v_and_b32_e32 v10, 8, v2
	v_and_b32_e32 v2, 3, v195
	v_lshl_add_u64 v[114:115], s[6:7], 0, v[104:105]
	v_or3_b32 v2, v8, v2, s13
	v_readlane_b32 s6, v254, 10
	v_lshlrev_b64 v[2:3], 9, v[2:3]
	v_readlane_b32 s7, v254, 11
	v_lshrrev_b32_e32 v108, 5, v195
	v_mov_b32_e32 v29, 0xc600
	v_lshl_add_u64 v[2:3], s[6:7], 0, v[2:3]
	s_add_i32 s7, 0, 0x12700
	s_movk_i32 s6, 0x210
	v_mov_b32_e32 v21, s7
	v_mad_u32_u24 v203, v108, s6, v21
	v_lshrrev_b32_e32 v21, 7, v195
	v_and_b32_e32 v21, 4, v21
	v_add_lshl_u32 v21, v21, v195, 4
	v_and_b32_e32 v109, 15, v195
	v_and_b32_e32 v9, 6, v7
	v_lshl_add_u64 v[116:117], v[2:3], 0, v[104:105]
	v_and_b32_e32 v3, 0x1f0, v4
	v_lshrrev_b32_e32 v12, 2, v195
	v_and_b32_e32 v204, 0x1f0, v21
	v_add_u32_e32 v21, 16, v108
	v_add_u32_e32 v24, 48, v108
	v_add_u32_e32 v27, 0x50, v108
	v_mad_u32_u24 v210, v108, s6, v29
	v_add_u32_e32 v29, 0x70, v108
	v_add_u32_e32 v33, 0xa00, v195
	v_and_b32_e32 v7, 64, v7
	v_or_b32_e32 v8, s13, v8
	v_and_b32_e32 v11, 48, v195
	v_add_u32_e32 v196, 0, v3
	v_and_b32_e32 v2, 0xf8, v12
	v_lshlrev_b32_e32 v205, 3, v21
	v_lshrrev_b32_e32 v21, 2, v21
	v_lshlrev_b32_e32 v206, 3, v24
	v_lshrrev_b32_e32 v24, 2, v24
	v_lshlrev_b32_e32 v208, 3, v27
	v_lshrrev_b32_e32 v27, 2, v27
	v_lshlrev_b32_e32 v212, 3, v29
	v_lshrrev_b32_e32 v29, 2, v29
	v_mul_u32_u24_e32 v32, 0x110, v109
	v_lshrrev_b32_e32 v122, 5, v33
	v_add_u32_e32 v33, 0xe00, v195
	s_lshl_b32 s24, s2, 7
	v_lshl_add_u32 v7, v8, 1, v7
	v_mul_u32_u24_e32 v197, 0x210, v2
	v_mad_u32_u24 v198, v2, s6, v196
	v_or_b32_e32 v199, 1, v2
	v_add_u32_e32 v13, s7, v11
	v_and_b32_e32 v2, 0x1f80, v5
; #define LAS __attribute__((address_space(3)))
; __device__ __forceinline__ void mixer_phase(LAS unsigned char* lds, bf16* U  , const bf16* V, const bf16* C, bf16* Bout,
;                                             const bf16* wsb, const float* sgu_b, const float* sgu_g, const bf16* pwT, const float* pool_scale, int G, int bid) {
;     ...
;                 for (int i = 0; i < 4; ++i) { const int id = tid + 512 * i; wv[i] = *(const v4u*)(wsb + (size_t)g * 16384 + (id >> 4) * 128 + (id & 15) * 8); }
;                 const int c8 = tid & 31;
; #pragma unroll
;                 for (int i = 0; i < 8; ++i) vv[i] = *(const v4u*)(V + (size_t)(r0 + (tid >> 5) + 16 * i) * D + g * 256 + c8 * 8);
;                 const f32x4 g0 = *(const f32x4*)(sgu_g + g * 256 + c8 * 8), g1 = *(const f32x4*)(sgu_g + g * 256 + c8 * 8 + 4);
; #pragma unroll
;                 for (int i = 0; i < 4; ++i) { const int id = tid + 512 * i; *(LAS v4u*)(lds + (id >> 4) * MX_WS_PITCH + (id & 15) * 16) = wv[i]; }
; #pragma unroll
;                 for (int i = 0; i < 8; ++i) { const int sr = (tid >> 5) + 16 * i;
;                     float x[8]; unpack8(vv[i], x);
;                     const float mean = stat[2 * sr], rstd = stat[2 * sr + 1];
;                     v4u w; w.x = pk2((x[0] - mean) * rstd * g0.x, (x[1] - mean) * rstd * g0.y); w.y = pk2((x[2] - mean) * rstd * g0.z, (x[3] - mean) * rstd * g0.w);
;                     w.z = pk2((x[4] - mean) * rstd * g1.x, (x[5] - mean) * rstd * g1.y); w.w = pk2((x[6] - mean) * rstd * g1.z, (x[7] - mean) * rstd * g1.w);
;                     { const v4u ws = ((sr >> 3) & 1) ? (v4u){w.z, w.w, w.x, w.y} : w;
;                       *(LAS v4u*)(lds + MX_T_OFF + sr * MX_T_PITCH + ((c8 + 4 * ((sr >> 4) & 1)) & 31) * 16) = ws; } }
;             }
;             __syncthreads();
;             v4u uu[8];
; #pragma unroll
;             for (int m = 0; m < 8; ++m) uu[m] = *(const v4u*)(U + (size_t)(r0 + 16 * m + fr) * D + g * 256 + 32 * wid + 8 * fq);
;             f32x4 acc[8][2];
; #pragma unroll
;             for (int m = 0; m < 8; ++m) { acc[m][0] = (f32x4){0.f, 0.f, 0.f, 0.f}; acc[m][1] = (f32x4){0.f, 0.f, 0.f, 0.f}; }
;             const int dch = 32 * wid + 8 * (fr >> 2) + (fr & 3);
; #pragma unroll 1
;             for (int k = 0; k < 4; ++k) {
;                 bf16x8 vf[2];
; #pragma unroll
;                 for (int n = 0; n < 2; ++n)
; #pragma unroll
	v_add_u32_e32 v4, 0x1000, v5
	v_add_u32_e32 v5, 0x3000, v5
	v_add_u32_e32 v14, 0x200, v195
	v_or_b32_e32 v16, 0x400, v195
	v_add_u32_e32 v18, 0x600, v195
	v_and_b32_e32 v21, 4, v21
	v_and_b32_e32 v24, 4, v24
	v_and_b32_e32 v27, 4, v27
	v_and_b32_e32 v29, 4, v29
	v_lshrrev_b32_e32 v124, 5, v33
	v_or_b32_e32 v33, 0x1000, v195
	s_add_i32 s36, s24, s12
	v_add3_u32 v220, v32, v11, 0
	v_bfe_u32 v11, v195, 4, 2
	v_and_b32_e32 v7, 0x1f0, v7
	s_movk_i32 s12, 0x1080
	v_or_b32_e32 v201, s13, v6
	v_and_b32_e32 v6, 0x7f80, v5
	v_lshrrev_b32_e32 v5, 4, v195
	v_lshrrev_b32_e32 v15, 4, v14
	v_lshrrev_b32_e32 v17, 4, v16
	v_lshrrev_b32_e32 v19, 4, v18
	v_add_lshl_u32 v21, v21, v195, 4
	v_add_lshl_u32 v24, v24, v195, 4
	v_add_lshl_u32 v27, v27, v195, 4
	v_add_u32_e32 v211, s7, v210
	v_add_lshl_u32 v29, v29, v195, 4
	v_or_b32_e32 v31, 8, v9
	s_movk_i32 s10, 0x11e0
	v_lshrrev_b32_e32 v126, 5, v33
	v_or_b32_e32 v12, 7, v12
	v_lshrrev_b32_e32 v128, 5, v14
	v_lshrrev_b32_e32 v130, 5, v16
	v_lshrrev_b32_e32 v132, 5, v18
	s_lshl_b32 s3, s3, 7
	v_mad_u32_u24 v7, v11, s12, v7
	v_add_u32_e32 v200, s7, v3
	v_and_b32_e32 v4, 0x3f80, v4
	v_mul_u32_u24_e32 v5, 0x110, v5
	v_mul_u32_u24_e32 v15, 0x110, v15
	v_mul_u32_u24_e32 v17, 0x110, v17
	v_mul_u32_u24_e32 v19, 0x110, v19
	v_mul_u32_u24_e32 v20, 0x210, v108
	v_add_u32_e32 v22, 0x2100, v203
	v_and_b32_e32 v21, 0x1f0, v21
	v_add_u32_e32 v23, 0x4200, v203
	v_add_u32_e32 v25, 0x6300, v203
	v_and_b32_e32 v24, 0x1f0, v24
	v_or_b32_e32 v118, 64, v108
	v_add_u32_e32 v26, 0x8400, v203
	v_add_u32_e32 v28, 0xa500, v203
	v_and_b32_e32 v27, 0x1f0, v27
	v_or_b32_e32 v120, 0x60, v108
	v_add_u32_e32 v30, 0x2100, v211
	v_and_b32_e32 v29, 0x1f0, v29
	s_movk_i32 s6, 0x1df
	s_movk_i32 s8, 0x3e0
	v_cmp_gt_u32_e64 s[10:11], s10, v33
	v_mul_u32_u24_e32 v33, 0x210, v122
	v_mul_u32_u24_e32 v34, 0x210, v124
	v_mul_u32_u24_e32 v35, 0x210, v126
	v_mul_u32_u24_e32 v12, 0x210, v12
	v_mul_u32_u24_e32 v36, 0x210, v109
	v_mul_u32_u24_e32 v14, 0x210, v128
	v_mul_u32_u24_e32 v16, 0x210, v130
	v_mul_u32_u24_e32 v18, 0x210, v132
	s_add_i32 s3, s3, 0
	v_or3_b32 v8, v7, v10, v9
	v_bitop3_b32 v7, v7, v31, v10 bitop3:0xf6
	v_add3_u32 v3, v197, v3, 0
	s_movk_i32 s54, 0x8800
	s_mov_b32 s25, 0
	v_cmp_eq_u32_e64 s[0:1], 0, v194
	v_lshlrev_b32_e32 v202, 3, v108
	v_lshlrev_b32_e32 v207, 3, v118
	v_lshlrev_b32_e32 v209, 3, v120
	v_or_b32_e32 v213, 16, v109
	v_or_b32_e32 v214, 32, v109
	v_or_b32_e32 v215, 48, v109
	v_or_b32_e32 v216, 64, v109
	v_or_b32_e32 v217, 0x50, v109
	v_or_b32_e32 v218, 0x60, v109
	v_or_b32_e32 v219, 0x70, v109
	v_cmp_lt_u32_e64 s[6:7], s6, v195
	v_cmp_gt_u32_e64 s[8:9], s8, v195
	v_mov_b32_e32 v125, v105
	v_mov_b32_e32 v127, v105
	s_add_i32 s3, s3, 0x22f00
	v_lshlrev_b32_e32 v134, 4, v194
	v_mov_b32_e32 v135, v105
	s_or_b32 s38, s36, 3
	s_lshl_b32 s66, s33, 7
	s_or_b32 s40, s36, 2
	s_or_b32 s44, s36, 1
	v_add_u32_e32 v221, 0, v8
	v_add_u32_e32 v222, 0, v7
	v_add_u32_e32 v223, 0x1ce0, v3
	v_mov_b32_e32 v224, 0x358637bd
	s_mov_b32 s67, 0xf800000
	v_mov_b32_e32 v225, 0x260
	s_mov_b64 s[48:49], 0x18000
	s_mov_b64 s[50:51], 0x28000
	s_mov_b64 s[52:53], 0x38000
	v_lshlrev_b32_e32 v104, 1, v2
	v_lshlrev_b32_e32 v136, 1, v4
	v_lshlrev_b32_e32 v138, 1, v6
	v_add_u32_e32 v226, v1, v5
	v_add_u32_e32 v227, v1, v15
	v_add_u32_e32 v228, v1, v17
	v_add_u32_e32 v229, v1, v19
	v_add_u32_e32 v230, v22, v21
	v_add_u32_e32 v231, v23, v204
	v_add_u32_e32 v232, v25, v24
	v_add_u32_e32 v233, v26, v204
	v_add_u32_e32 v234, v28, v27
	v_add_u32_e32 v235, v30, v29
	s_mov_b32 s68, 0x5040100
	v_lshlrev_b32_e32 v140, 1, v0
	s_mov_b32 s55, -1
	v_add_u32_e32 v236, v196, v20
	v_add_u32_e32 v237, v196, v14
	v_add_u32_e32 v238, v196, v16
	v_add_u32_e32 v239, v196, v18
	v_add_u32_e32 v240, v196, v33
	v_add_u32_e32 v241, v196, v34
	v_add_u32_e32 v242, v196, v35
	v_add_u32_e32 v243, v200, v12
	v_add_u32_e32 v244, v13, v36
	s_mov_b32 s69, s2

; __device__ __forceinline__ unsigned xb_ld(unsigned* p)              { return __hip_atomic_load(p, __ATOMIC_RELAXED, __HIP_MEMORY_SCOPE_AGENT); }
; __device__ __forceinline__ unsigned xb_add(unsigned* p, unsigned v) { return __hip_atomic_fetch_add(p, v, __ATOMIC_RELAXED, __HIP_MEMORY_SCOPE_AGENT); }
; #define XB_SPIN(cond, bar) do { unsigned _sp = 0; while (cond) { __builtin_amdgcn_s_sleep(1); \
;     if ((++_sp & 255u) == 0u) { if (xb_ld(&(bar)[XB_TMO])) break; if (_sp > XB_SPIN_CAP) { atomicAdd(&(bar)[XB_TMO], 1u); break; } } } } while (0)
; #define SEAM(k) do { if (IN(k) && IN((k) + 1)) { xcd_barrier(xbar); } } while (0)
; __device__ __forceinline__ void xcd_barrier(const XcdBarrier& b) {
;     asm volatile("s_waitcnt vmcnt(0)" ::: "memory");
;     __syncthreads();
;     if (threadIdx.x == 0) {
;         unsigned* bar = b.bar;
;         __builtin_amdgcn_s_waitcnt(0);
;         unsigned nloc = b.st[0], nx = b.st[1];
;         if (nloc == 0u) { xcd_barrier_complete(bar, b.x, nloc, nx); b.st[0] = nloc; b.st[1] = nx; }
;         const unsigned old = xb_add(&bar[XB_XSUB(b.x)], 1u);
;         const unsigned gen = old / nloc;
;         if (old + 1u == (gen + 1u) * nloc) {
;             __builtin_amdgcn_fence(__ATOMIC_RELEASE, "agent");
;             asm volatile("s_waitcnt vmcnt(0)" ::: "memory");
;             const unsigned og = xb_add(&bar[XB_TOP], 1u);
;             const unsigned tg = og / nx;
;             if (og + 1u == (tg + 1u) * nx) xb_add(&bar[XB_TOPGEN], 1u);
;             else XB_SPIN(xb_ld(&bar[XB_TOPGEN]) == tg, bar);
;             __builtin_amdgcn_fence(__ATOMIC_ACQUIRE, "agent");
;             xb_add(&bar[XB_XGEN(b.x)], 1u);
;             asm volatile("s_waitcnt vmcnt(0)" ::: "memory");
;         } else {
;             XB_SPIN(xb_ld(&bar[XB_XGEN(b.x)]) == gen, bar);
;             __builtin_amdgcn_fence(__ATOMIC_ACQUIRE, "agent");
;             asm volatile("s_waitcnt vmcnt(0)" ::: "memory");
;         }
; __global__ void __launch_bounds__(NWAVES * 64, 2) mk_fwd(Args a) {
;     ...
;     if (IN(5)) mixer_phase(lds, S1, S2, S3, BB, SGW, a.in[I_SGUB], a.in[I_SGUG], PWT, a.in[I_POOLS], G, bid);
;     SEAM(5);
.LBB0_719:
	s_mov_b32 s2, s98
	s_cmp_gt_i32 s31, 6
	s_cselect_b64 s[0:1], -1, 0
	s_and_b64 s[4:5], s[14:15], s[0:1]
	s_andn2_b64 vcc, exec, s[4:5]
	s_cbranch_vccnz .LBB0_769
	s_waitcnt vmcnt(0)
	s_barrier
	v_cmp_eq_u32_e32 vcc, 0, v195
	s_and_saveexec_b64 s[4:5], vcc
	s_cbranch_execz .Ltb769_done
	s_and_b32 s3, s2, 7
	s_lshl_b32 s3, s3, 3
	s_bfe_u32 s13, s2, 0x30003
	s_or_b32 s3, s3, s13
	s_lshl_b32 s3, s3, 5
	s_add_u32 s8, s28, 0x3903600
	s_addc_u32 s9, s29, 0
	v_mov_b32_e32 v0, s3
	v_mov_b32_e32 v1, 1
	v_mov_b32_e32 v2, 16
	s_mov_b32 s15, 0
	s_cmp_eq_u32 s99, 1
	s_cbranch_scc1 .Ltb769_fast
	buffer_wbl2 sc1
	s_waitcnt vmcnt(0)
	global_atomic_add v0, v1, s[8:9]

; __device__ __forceinline__ unsigned xb_ld(unsigned* p)              { return __hip_atomic_load(p, __ATOMIC_RELAXED, __HIP_MEMORY_SCOPE_AGENT); }
; __device__ __forceinline__ unsigned xb_add(unsigned* p, unsigned v) { return __hip_atomic_fetch_add(p, v, __ATOMIC_RELAXED, __HIP_MEMORY_SCOPE_AGENT); }
; #define XB_SPIN(cond, bar) do { unsigned _sp = 0; while (cond) { __builtin_amdgcn_s_sleep(1); \
;     if ((++_sp & 255u) == 0u) { if (xb_ld(&(bar)[XB_TMO])) break; if (_sp > XB_SPIN_CAP) { atomicAdd(&(bar)[XB_TMO], 1u); break; } } } } while (0)
; __device__ __forceinline__ void xcd_barrier(const XcdBarrier& b) {
;     ...
;         const unsigned old = xb_add(&bar[XB_XSUB(b.x)], 1u);
;         const unsigned gen = old / nloc;
;         if (old + 1u == (gen + 1u) * nloc) {
;             __builtin_amdgcn_fence(__ATOMIC_RELEASE, "agent");
;             asm volatile("s_waitcnt vmcnt(0)" ::: "memory");
;             const unsigned og = xb_add(&bar[XB_TOP], 1u);
;             const unsigned tg = og / nx;
;             if (og + 1u == (tg + 1u) * nx) xb_add(&bar[XB_TOPGEN], 1u);
;             else XB_SPIN(xb_ld(&bar[XB_TOPGEN]) == tg, bar);
;             __builtin_amdgcn_fence(__ATOMIC_ACQUIRE, "agent");
;             xb_add(&bar[XB_XGEN(b.x)], 1u);
;             asm volatile("s_waitcnt vmcnt(0)" ::: "memory");
;         } else {
;             XB_SPIN(xb_ld(&bar[XB_XGEN(b.x)]) == gen, bar);
;             __builtin_amdgcn_fence(__ATOMIC_ACQUIRE, "agent");
;             asm volatile("s_waitcnt vmcnt(0)" ::: "memory");
;         }
;     }
;     __syncthreads();
; }
; __global__ void __launch_bounds__(NWAVES * 64, 2) mk_fwd(Args a) {
;     ...
;         { pg8::Gemm g{S1, WOA, M, D, D}; pg8::StaticOrder S; S.init(M, D, G, bid); EpiN<0, true, false, false> E{S2, S4, nullptr, nullptr};
;           pg8::gemm_phase<EpiN<0, true, false, false>, pg8::StaticOrder, true, true, NT_NARROW, ZZ, PEELK>(lds, g, S, E); }
.Ltb769_done:
	s_or_b64 exec, exec, s[4:5]
	s_barrier
.LBB0_769:
	s_cmp_lt_i32 s30, 7
	s_cselect_b64 s[4:5], -1, 0
	s_and_b64 s[4:5], s[4:5], s[0:1]
	s_andn2_b64 vcc, exec, s[4:5]
	s_cbranch_vccnz .LBB0_818
	s_waitcnt vmcnt(0)
	v_lshrrev_b32_e32 v2, 5, v195
	v_lshrrev_b32_e32 v4, 1, v195
	v_and_b32_e32 v2, 4, v2
	v_bfe_u32 v3, v195, 2, 2
	v_and_b32_e32 v147, 24, v4
	v_lshlrev_b32_e32 v0, 4, v195
	v_and_b32_e32 v1, 32, v195
	v_bfe_u32 v146, v195, 2, 4
	v_or3_b32 v2, v2, v3, v147
	v_lshrrev_b32_e32 v3, 3, v195
	s_movk_i32 s0, 0x70
	v_bitop3_b32 v144, v0, v1, 48 bitop3:0x6c
	v_and_b32_e32 v145, 64, v195
	v_and_or_b32 v4, v3, s0, v146
	s_movk_i32 s0, 0x60
	v_add_u32_e32 v148, 0x2000, v0
	v_or_b32_e32 v1, v144, v145
	v_and_or_b32 v3, v3, s0, v2
	v_lshrrev_b32_e32 v0, 7, v148
	s_movk_i32 s0, 0xf0
	v_lshl_or_b32 v154, v3, 11, v1
	v_and_or_b32 v3, v0, s0, v146
	s_movk_i32 s0, 0xe0
	v_and_or_b32 v0, v0, s0, v2
	v_lshl_or_b32 v152, v4, 11, v1
	v_lshl_or_b32 v156, v3, 11, v1
	v_lshl_or_b32 v158, v0, 11, v1
	v_lshlrev_b32_e32 v0, 6, v195
	v_lshlrev_b32_e32 v1, 2, v195
	v_lshlrev_b32_e32 v150, 1, v147
	v_and_b32_e32 v0, 0x3c0, v0
	v_and_b32_e32 v1, 32, v1
	s_cmpk_lt_i32 s2, 0x200
	v_readfirstlane_b32 s12, v195
	v_and_b32_e32 v149, 15, v195
	s_cselect_b64 s[6:7], -1, 0
	s_cmpk_gt_i32 s2, 0x1ff
	v_bitop3_b32 v151, v150, v1, v0 bitop3:0x36
	s_cbranch_scc1 .LBB0_794
	s_ashr_i32 s3, s2, 31
	s_lshr_b32 s0, s3, 29
	s_add_i32 s8, s2, s0
	s_and_b32 s0, s8, -8
	s_sub_i32 s10, s2, s0
	s_cmp_gt_i32 s10, -1
	s_cbranch_scc0 .LBB0_773
	s_lshl_b32 s9, s10, 6
	s_cbranch_execz .LBB0_774
	s_branch .LBB0_775

; __device__ __forceinline__ unsigned xb_ld(unsigned* p)              { return __hip_atomic_load(p, __ATOMIC_RELAXED, __HIP_MEMORY_SCOPE_AGENT); }
; __device__ __forceinline__ unsigned xb_add(unsigned* p, unsigned v) { return __hip_atomic_fetch_add(p, v, __ATOMIC_RELAXED, __HIP_MEMORY_SCOPE_AGENT); }
; #define XB_SPIN(cond, bar) do { unsigned _sp = 0; while (cond) { __builtin_amdgcn_s_sleep(1); \
;     if ((++_sp & 255u) == 0u) { if (xb_ld(&(bar)[XB_TMO])) break; if (_sp > XB_SPIN_CAP) { atomicAdd(&(bar)[XB_TMO], 1u); break; } } } } while (0)
; __device__ __forceinline__ void xcd_barrier(const XcdBarrier& b) {
;     asm volatile("s_waitcnt vmcnt(0)" ::: "memory");
;     __syncthreads();
;     if (threadIdx.x == 0) {
;         unsigned* bar = b.bar;
;         __builtin_amdgcn_s_waitcnt(0);
;         unsigned nloc = b.st[0], nx = b.st[1];
;         if (nloc == 0u) { xcd_barrier_complete(bar, b.x, nloc, nx); b.st[0] = nloc; b.st[1] = nx; }
;         const unsigned old = xb_add(&bar[XB_XSUB(b.x)], 1u);
;         const unsigned gen = old / nloc;
;         if (old + 1u == (gen + 1u) * nloc) {
;             __builtin_amdgcn_fence(__ATOMIC_RELEASE, "agent");
;             asm volatile("s_waitcnt vmcnt(0)" ::: "memory");
;             const unsigned og = xb_add(&bar[XB_TOP], 1u);
;             const unsigned tg = og / nx;
;             if (og + 1u == (tg + 1u) * nx) xb_add(&bar[XB_TOPGEN], 1u);
;             else XB_SPIN(xb_ld(&bar[XB_TOPGEN]) == tg, bar);
;             __builtin_amdgcn_fence(__ATOMIC_ACQUIRE, "agent");
;             xb_add(&bar[XB_XGEN(b.x)], 1u);
;             asm volatile("s_waitcnt vmcnt(0)" ::: "memory");
;         } else {
;             XB_SPIN(xb_ld(&bar[XB_XGEN(b.x)]) == gen, bar);
;             __builtin_amdgcn_fence(__ATOMIC_ACQUIRE, "agent");
;             asm volatile("s_waitcnt vmcnt(0)" ::: "memory");
;         }
.LBB0_818:
	s_cmp_gt_i32 s31, 7
	s_cselect_b64 s[0:1], -1, 0
	s_and_b64 s[4:5], s[4:5], s[0:1]
	v_readlane_b32 s68, v254, 8
	v_readlane_b32 s70, v254, 6
	v_readlane_b32 s76, v254, 4
	s_andn2_b64 vcc, exec, s[4:5]
	v_readlane_b32 s69, v254, 9
	v_readlane_b32 s71, v254, 7
	v_readlane_b32 s77, v254, 5
	s_cbranch_vccnz .LBB0_868
	s_waitcnt vmcnt(0)
	s_barrier
	v_cmp_eq_u32_e32 vcc, 0, v195
	s_and_saveexec_b64 s[4:5], vcc
	s_cbranch_execz .Ltb868_done
	s_and_b32 s3, s2, 7
	s_lshl_b32 s3, s3, 3
	s_bfe_u32 s13, s2, 0x30003
	s_or_b32 s3, s3, s13
	s_lshl_b32 s3, s3, 5
	s_add_u32 s8, s28, 0x3903600
	s_addc_u32 s9, s29, 0
	v_mov_b32_e32 v0, s3
	v_mov_b32_e32 v1, 1
	v_mov_b32_e32 v2, 20
	s_mov_b32 s15, 0
	s_cmp_eq_u32 s99, 1
	s_cbranch_scc1 .Ltb868_fast
	buffer_wbl2 sc1
	s_waitcnt vmcnt(0)
	global_atomic_add v0, v1, s[8:9]

;     const int tid = threadIdx.x, wid = __builtin_amdgcn_readfirstlane(tid >> 6), lane = tid & 63, wr = wid >> 2, wc = wid & 3, fr = lane & 15, fq = lane >> 4;
;     const int K = g.K, nt = K / BK;
;     unsigned voffA[2], voffB[2];
; #pragma unroll
;     for (int i = 0; i < 2; ++i) { int R, C; stage_rc(tid * 16 + i * 8192, R, C); const int Rb = Epi::PERM ? ((R & ~31) + perm32(R & 31)) : R;
;         voffA[i] = (unsigned)(R * K + C) * 2u; voffB[i] = (unsigned)(Rb * K + C) * 2u; }
;     const size_t kstep = (size_t)(BK * 2);
;     const size_t hstep = (size_t)HALF * K * 2;
;     const size_t tstep = 2 * hstep;
;     const unsigned ldsw = (unsigned)wid * 1024u;
;     const int aoff = lds_byte(wr * 64 + fr, fq * 8), boff = lds_byte(wc * 32 + fr, fq * 8);
; __global__ void __launch_bounds__(NWAVES * 64, 2) mk_fwd(Args a) {
;     ...
;     if (IN(7)) { pg8::Gemm g{S2, WO, M, D, D}; pg8::StaticOrder S; S.init(M, D, G, bid); EpiN<0, false, false, true> E{S3, nullptr, nullptr, PART};
;         pg8::gemm_phase<EpiN<0, false, false, true>, pg8::StaticOrder, true, true, NT_NARROW, ZZ, PEELK>(lds, g, S, E); }
.LBB0_868:
	s_add_u32 s22, s28, 0x15000000
	s_addc_u32 s23, s29, 0
	s_cmp_lt_i32 s30, 8
	s_cselect_b64 s[4:5], -1, 0
	s_and_b64 s[4:5], s[4:5], s[0:1]
	s_andn2_b64 vcc, exec, s[4:5]
	s_cbranch_vccnz .LBB0_893
	s_cmpk_gt_i32 s2, 0x1ff
	v_readfirstlane_b32 s6, v195
	s_cbranch_scc1 .LBB0_893
	s_ashr_i32 s3, s2, 31
	s_lshr_b32 s0, s3, 29
	s_add_i32 s8, s2, s0
	s_and_b32 s0, s8, -8
	s_sub_i32 s9, s2, s0
	s_cmp_gt_i32 s9, -1
	s_cbranch_scc0 .LBB0_872
	s_lshl_b32 s7, s9, 6
	s_cbranch_execz .LBB0_873
	s_branch .LBB0_874

; __device__ __forceinline__ unsigned xb_ld(unsigned* p)              { return __hip_atomic_load(p, __ATOMIC_RELAXED, __HIP_MEMORY_SCOPE_AGENT); }
; __device__ __forceinline__ unsigned xb_add(unsigned* p, unsigned v) { return __hip_atomic_fetch_add(p, v, __ATOMIC_RELAXED, __HIP_MEMORY_SCOPE_AGENT); }
; #define XB_SPIN(cond, bar) do { unsigned _sp = 0; while (cond) { __builtin_amdgcn_s_sleep(1); \
;     if ((++_sp & 255u) == 0u) { if (xb_ld(&(bar)[XB_TMO])) break; if (_sp > XB_SPIN_CAP) { atomicAdd(&(bar)[XB_TMO], 1u); break; } } } } while (0)
; __device__ __forceinline__ void xcd_barrier(const XcdBarrier& b) {
;     asm volatile("s_waitcnt vmcnt(0)" ::: "memory");
;     __syncthreads();
;     if (threadIdx.x == 0) {
;         unsigned* bar = b.bar;
;         __builtin_amdgcn_s_waitcnt(0);
;         unsigned nloc = b.st[0], nx = b.st[1];
;         if (nloc == 0u) { xcd_barrier_complete(bar, b.x, nloc, nx); b.st[0] = nloc; b.st[1] = nx; }
;         const unsigned old = xb_add(&bar[XB_XSUB(b.x)], 1u);
;         const unsigned gen = old / nloc;
;         if (old + 1u == (gen + 1u) * nloc) {
;             __builtin_amdgcn_fence(__ATOMIC_RELEASE, "agent");
;             asm volatile("s_waitcnt vmcnt(0)" ::: "memory");
;             const unsigned og = xb_add(&bar[XB_TOP], 1u);
;             const unsigned tg = og / nx;
;             if (og + 1u == (tg + 1u) * nx) xb_add(&bar[XB_TOPGEN], 1u);
;             else XB_SPIN(xb_ld(&bar[XB_TOPGEN]) == tg, bar);
;             __builtin_amdgcn_fence(__ATOMIC_ACQUIRE, "agent");
;             xb_add(&bar[XB_XGEN(b.x)], 1u);
;             asm volatile("s_waitcnt vmcnt(0)" ::: "memory");
;         } else {
;             XB_SPIN(xb_ld(&bar[XB_XGEN(b.x)]) == gen, bar);
;             __builtin_amdgcn_fence(__ATOMIC_ACQUIRE, "agent");
;             asm volatile("s_waitcnt vmcnt(0)" ::: "memory");
;         }
.LBB0_893:
	s_cmp_gt_i32 s31, 8
	s_cselect_b64 s[0:1], -1, 0
	s_and_b64 s[4:5], s[4:5], s[0:1]
	s_andn2_b64 vcc, exec, s[4:5]
	s_cbranch_vccnz .LBB0_943
	s_waitcnt vmcnt(0)
	s_barrier
	v_cmp_eq_u32_e32 vcc, 0, v195
	s_and_saveexec_b64 s[4:5], vcc
	s_cbranch_execz .Ltb943_done
	s_and_b32 s3, s2, 7
	s_lshl_b32 s3, s3, 3
	s_bfe_u32 s13, s2, 0x30003
	s_or_b32 s3, s3, s13
	s_lshl_b32 s3, s3, 5
	s_add_u32 s8, s28, 0x3903600
	s_addc_u32 s9, s29, 0
	v_mov_b32_e32 v0, s3
	v_mov_b32_e32 v1, 1
	v_mov_b32_e32 v2, 24
	s_mov_b32 s15, 0
	s_cmp_eq_u32 s99, 1
	s_cbranch_scc1 .Ltb943_fast
	buffer_wbl2 sc1
	s_waitcnt vmcnt(0)
	global_atomic_add v0, v1, s[8:9]

; template <bool SRC_F32, int R> __device__ __forceinline__ void ew_load(EwSet<SRC_F32, R>& S, int rb, const float* hsrc32, const bf16* hsrcb, const bf16* f, const float* part, int lane) {
; #pragma unroll
;     for (int i = 0; i < R; ++i) S.p[i] = (lane < 16) ? part[(size_t)(rb + i) * 16 + lane] : 0.f;
; #pragma unroll
;     for (int i = 0; i < R; ++i)
; #pragma unroll
;         for (int j = 0; j < 4; ++j) {
;             S.fw[i][j] = ((const v2u*)(f + (size_t)(rb + i) * D) + lane)[64 * j];
;             if constexpr (SRC_F32) S.h32[i][j] = __builtin_nontemporal_load((const f32x4*)(hsrc32 + (size_t)(rb + i) * D) + lane + 64 * j);
;             else S.hb[i][j] = ((const v2u*)(hsrcb + (size_t)(rb + i) * D) + lane)[64 * j];
;         }
; }
; template <bool SRC_F32, bool FINAL, int R> __device__ __forceinline__ void ew_compute(const EwSet<SRC_F32, R>& S, int rb, const f32x4 (&g)[4], bf16* hb_out, float* out32, float scale, float* rs_out, int lane) {
; #pragma unroll
;     for (int i = 0; i < R; ++i) {
;         float q = S.p[i];
;         q += __shfl_xor(q, 1); q += __shfl_xor(q, 2); q += __shfl_xor(q, 4); q += __shfl_xor(q, 8);
;         const float ss = __shfl(q, 0);
;         const float rs = scale / sqrtf(ss * (1.f / D) + EPS);
;         float s2 = 0.f;
; #pragma unroll
;         for (int j = 0; j < 4; ++j) {
;             f32x4 h;
;             if constexpr (SRC_F32) h = S.h32[i][j];
;             else { const v2u hw = S.hb[i][j]; h.x = bf_lo(hw.x); h.y = bf_hi(hw.x); h.z = bf_lo(hw.y); h.w = bf_hi(hw.y); }
;             const v2u fw = S.fw[i][j];
;             f32x4 v; v.x = h.x + bf_lo(fw.x) * rs * g[j].x; v.y = h.y + bf_hi(fw.x) * rs * g[j].y; v.z = h.z + bf_lo(fw.y) * rs * g[j].z; v.w = h.w + bf_hi(fw.y) * rs * g[j].w;
;             if (FINAL) __builtin_nontemporal_store(v, (f32x4*)(out32 + (size_t)(rb + i) * D) + lane + 64 * j);
;             else { v2u o; o.x = pk2(v.x, v.y); o.y = pk2(v.z, v.w); ((v2u*)(hb_out + (size_t)(rb + i) * D) + lane)[64 * j] = o; s2 += (v.x * v.x + v.y * v.y) + (v.z * v.z + v.w * v.w); }
;         }
;         if (!FINAL) { const float tot = wave_sum(s2); if (lane == 0) rs_out[rb + i] = 1.0f / sqrtf(tot * (1.f / D) + EPS); }
; __global__ void __launch_bounds__(NWAVES * 64, 2) mk_fwd(Args a) {
;     ...
;     if (IN(8)) ew_phase<false, false>(nullptr, HB, HB, nullptr, S3, PART, a.in[I_MIXPOST], 1.0f, RS, gw, NGW, lane);
.LBB0_943:
	s_cmp_lt_i32 s30, 9
	s_cselect_b64 s[4:5], -1, 0
	s_and_b64 s[8:9], s[4:5], s[0:1]
	s_andn2_b64 vcc, exec, s[8:9]
	s_cbranch_vccnz .LBB0_989
	s_waitcnt vmcnt(0) lgkmcnt(0)
	s_add_u32 s22, s84, 0xffffff10
	s_addc_u32 s23, s85, -1
	s_load_dwordx2 s[26:27], s[22:23], 0x88
	s_add_u32 s0, s28, 0x5000000
	s_addc_u32 s1, s29, 0
	s_add_u32 s4, s28, 0x15000000
	s_addc_u32 s5, s29, 0
	s_add_u32 s6, s28, 0x3700000
	s_addc_u32 s7, s29, 0
	s_add_u32 s14, s28, 0x3910000
	s_addc_u32 s15, s29, 0
	v_and_b32_e32 v0, 63, v195
	v_lshlrev_b32_e32 v1, 5, v0
	s_waitcnt lgkmcnt(0)
	global_load_dwordx4 v[2:5], v1, s[26:27]
	global_load_dwordx4 v[6:9], v1, s[26:27] offset:16
	global_load_dwordx4 v[10:13], v1, s[26:27] offset:2048
	global_load_dwordx4 v[14:17], v1, s[26:27] offset:2064
	s_and_b32 s26, s2, 7
	s_lshl_b32 s26, s26, 4
	s_bfe_u32 s27, s2, 0x30003
	s_add_u32 s26, s26, s27
	s_lshl_b32 s26, s26, 8
	s_lshr_b32 s27, s2, 6
	s_lshl_b32 s27, s27, 6
	s_add_u32 s26, s26, s27
	v_readfirstlane_b32 s27, v195
	s_lshr_b32 s27, s27, 6
	s_lshl_b32 s27, s27, 3
	s_add_u32 s26, s26, s27
	s_add_u32 s27, s26, 0
	s_lshl_b32 s22, s27, 11
	v_lshl_add_u32 v18, v0, 4, s22
	v_add_u32_e32 v19, 0x1000, v18
	s_lshl_b32 s22, s27, 6
	v_lshl_add_u32 v20, v0, 2, s22
	s_lshl_b32 s22, s27, 2
	v_lshl_add_u32 v21, v0, 2, s22
	global_load_dwordx4 v[32:35], v18, s[0:1]
	global_load_dwordx4 v[36:39], v18, s[0:1] offset:1024
	global_load_dwordx4 v[64:67], v18, s[4:5]
	global_load_dwordx4 v[68:71], v18, s[4:5] offset:1024
	global_load_dwordx4 v[40:43], v18, s[0:1] offset:2048
	global_load_dwordx4 v[44:47], v18, s[0:1] offset:3072
	global_load_dwordx4 v[72:75], v18, s[4:5] offset:2048
	global_load_dwordx4 v[76:79], v18, s[4:5] offset:3072
	global_load_dwordx4 v[48:51], v19, s[0:1]
	global_load_dwordx4 v[52:55], v19, s[0:1] offset:1024
	global_load_dwordx4 v[80:83], v19, s[4:5]
	global_load_dwordx4 v[84:87], v19, s[4:5] offset:1024
	global_load_dwordx4 v[56:59], v19, s[0:1] offset:2048
	global_load_dwordx4 v[60:63], v19, s[0:1] offset:3072
	global_load_dwordx4 v[88:91], v19, s[4:5] offset:2048
	global_load_dwordx4 v[92:95], v19, s[4:5] offset:3072
	global_load_dword v96, v20, s[6:7]
	s_add_u32 s27, s26, 4
	s_lshl_b32 s22, s27, 11
	v_lshl_add_u32 v23, v0, 4, s22
	v_add_u32_e32 v24, 0x1000, v23
	s_lshl_b32 s22, s27, 6
	v_lshl_add_u32 v25, v0, 2, s22
	s_lshl_b32 s22, s27, 2
	v_lshl_add_u32 v26, v0, 2, s22
	global_load_dwordx4 v[100:103], v23, s[0:1]
	global_load_dwordx4 v[104:107], v23, s[0:1] offset:1024
	global_load_dwordx4 v[132:135], v23, s[4:5]
	global_load_dwordx4 v[136:139], v23, s[4:5] offset:1024
	global_load_dwordx4 v[108:111], v23, s[0:1] offset:2048
	global_load_dwordx4 v[112:115], v23, s[0:1] offset:3072
	global_load_dwordx4 v[140:143], v23, s[4:5] offset:2048
	global_load_dwordx4 v[144:147], v23, s[4:5] offset:3072
	global_load_dwordx4 v[116:119], v24, s[0:1]
	global_load_dwordx4 v[120:123], v24, s[0:1] offset:1024
	global_load_dwordx4 v[148:151], v24, s[4:5]
	global_load_dwordx4 v[152:155], v24, s[4:5] offset:1024
	global_load_dwordx4 v[124:127], v24, s[0:1] offset:2048
	global_load_dwordx4 v[128:131], v24, s[0:1] offset:3072
	global_load_dwordx4 v[156:159], v24, s[4:5] offset:2048
	global_load_dwordx4 v[160:163], v24, s[4:5] offset:3072
	global_load_dword v164, v25, s[6:7]
	s_waitcnt vmcnt(17)
	v_add_f32_dpp v96, v96, v96 quad_perm:[1,0,3,2] row_mask:0xf bank_mask:0xf
	s_nop 1
	v_add_f32_dpp v96, v96, v96 quad_perm:[2,3,0,1] row_mask:0xf bank_mask:0xf
	s_nop 1
	v_add_f32_dpp v96, v96, v96 row_half_mirror row_mask:0xf bank_mask:0xf
	s_nop 1
	v_add_f32_dpp v96, v96, v96 row_mirror row_mask:0xf bank_mask:0xf
	s_nop 1
	v_mul_f32_e32 v96, 0x3a800000, v96
	v_add_f32_e32 v96, 0x358637bd, v96
	v_rsq_f32_e32 v96, v96
	s_nop 0
	v_readlane_b32 s3, v96, 0
	v_readlane_b32 s24, v96, 16
	v_readlane_b32 s98, v96, 32
	v_readlane_b32 s101, v96, 48
	s_nop 1
	v_mov_b32_e32 v184, 0
	v_mov_b32_e32 v185, 0
	v_mov_b32_e32 v186, 0
	v_mov_b32_e32 v187, 0
	v_lshlrev_b32_e32 v168, 16, v32
	v_and_b32_e32 v169, 0xffff0000, v32
	v_lshlrev_b32_e32 v170, 16, v64
	v_and_b32_e32 v171, 0xffff0000, v64
	v_mul_f32_e32 v170, s3, v170
	v_mul_f32_e32 v171, s3, v171
	v_fma_f32 v168, v170, v2, v168
	v_fma_f32 v169, v171, v3, v169
	v_fma_f32 v184, v168, v168, v184
	v_fma_f32 v184, v169, v169, v184
	v_cvt_pk_bf16_f32 v32, v168, v169
	v_lshlrev_b32_e32 v168, 16, v33
	v_and_b32_e32 v169, 0xffff0000, v33
	v_lshlrev_b32_e32 v170, 16, v65
	v_and_b32_e32 v171, 0xffff0000, v65
	v_mul_f32_e32 v170, s3, v170
	v_mul_f32_e32 v171, s3, v171
	v_fma_f32 v168, v170, v4, v168
	v_fma_f32 v169, v171, v5, v169
	v_fma_f32 v184, v168, v168, v184
	v_fma_f32 v184, v169, v169, v184
	v_cvt_pk_bf16_f32 v33, v168, v169
	v_lshlrev_b32_e32 v168, 16, v34
	v_and_b32_e32 v169, 0xffff0000, v34
	v_lshlrev_b32_e32 v170, 16, v66
	v_and_b32_e32 v171, 0xffff0000, v66
	v_mul_f32_e32 v170, s3, v170
	v_mul_f32_e32 v171, s3, v171
	v_fma_f32 v168, v170, v6, v168
	v_fma_f32 v169, v171, v7, v169
	v_fma_f32 v184, v168, v168, v184
	v_fma_f32 v184, v169, v169, v184
	v_cvt_pk_bf16_f32 v34, v168, v169
	v_lshlrev_b32_e32 v168, 16, v35
	v_and_b32_e32 v169, 0xffff0000, v35
	v_lshlrev_b32_e32 v170, 16, v67
	v_and_b32_e32 v171, 0xffff0000, v67
	v_mul_f32_e32 v170, s3, v170
	v_mul_f32_e32 v171, s3, v171
	v_fma_f32 v168, v170, v8, v168
	v_fma_f32 v169, v171, v9, v169
	v_fma_f32 v184, v168, v168, v184
	v_fma_f32 v184, v169, v169, v184
	v_cvt_pk_bf16_f32 v35, v168, v169
	v_lshlrev_b32_e32 v168, 16, v36
	v_and_b32_e32 v169, 0xffff0000, v36
	v_lshlrev_b32_e32 v170, 16, v68
	v_and_b32_e32 v171, 0xffff0000, v68
	v_mul_f32_e32 v170, s3, v170
	v_mul_f32_e32 v171, s3, v171
; __device__ __forceinline__ float bf_lo(unsigned w) { return __uint_as_float(w << 16); }
; __device__ __forceinline__ float bf_hi(unsigned w) { return __uint_as_float(w & 0xffff0000u); }
; __device__ __forceinline__ unsigned pk2(float lo, float hi) { bf16x2_t r = __builtin_convertvector((f32x2_t){lo, hi}, bf16x2_t); return __builtin_bit_cast(unsigned, r); }
; template <bool SRC_F32, bool FINAL, int R> __device__ __forceinline__ void ew_compute(const EwSet<SRC_F32, R>& S, int rb, const f32x4 (&g)[4], bf16* hb_out, float* out32, float scale, float* rs_out, int lane) {
;     ...
; #pragma unroll
;         for (int j = 0; j < 4; ++j) {
;             f32x4 h;
;             if constexpr (SRC_F32) h = S.h32[i][j];
;             else { const v2u hw = S.hb[i][j]; h.x = bf_lo(hw.x); h.y = bf_hi(hw.x); h.z = bf_lo(hw.y); h.w = bf_hi(hw.y); }
;             const v2u fw = S.fw[i][j];
;             f32x4 v; v.x = h.x + bf_lo(fw.x) * rs * g[j].x; v.y = h.y + bf_hi(fw.x) * rs * g[j].y; v.z = h.z + bf_lo(fw.y) * rs * g[j].z; v.w = h.w + bf_hi(fw.y) * rs * g[j].w;
;             if (FINAL) __builtin_nontemporal_store(v, (f32x4*)(out32 + (size_t)(rb + i) * D) + lane + 64 * j);
;             else { v2u o; o.x = pk2(v.x, v.y); o.y = pk2(v.z, v.w); ((v2u*)(hb_out + (size_t)(rb + i) * D) + lane)[64 * j] = o; s2 += (v.x * v.x + v.y * v.y) + (v.z * v.z + v.w * v.w); }
;         }
;         if (!FINAL) { const float tot = wave_sum(s2); if (lane == 0) rs_out[rb + i] = 1.0f / sqrtf(tot * (1.f / D) + EPS); }
	v_fma_f32 v168, v170, v10, v168
	v_fma_f32 v169, v171, v11, v169
	v_fma_f32 v184, v168, v168, v184
	v_fma_f32 v184, v169, v169, v184
	v_cvt_pk_bf16_f32 v36, v168, v169
	v_lshlrev_b32_e32 v168, 16, v37
	v_and_b32_e32 v169, 0xffff0000, v37
	v_lshlrev_b32_e32 v170, 16, v69
	v_and_b32_e32 v171, 0xffff0000, v69
	v_mul_f32_e32 v170, s3, v170
	v_mul_f32_e32 v171, s3, v171
	v_fma_f32 v168, v170, v12, v168
	v_fma_f32 v169, v171, v13, v169
	v_fma_f32 v184, v168, v168, v184
	v_fma_f32 v184, v169, v169, v184
	v_cvt_pk_bf16_f32 v37, v168, v169
	v_lshlrev_b32_e32 v168, 16, v38
	v_and_b32_e32 v169, 0xffff0000, v38
	v_lshlrev_b32_e32 v170, 16, v70
	v_and_b32_e32 v171, 0xffff0000, v70
	v_mul_f32_e32 v170, s3, v170
	v_mul_f32_e32 v171, s3, v171
	v_fma_f32 v168, v170, v14, v168
	v_fma_f32 v169, v171, v15, v169
	v_fma_f32 v184, v168, v168, v184
	v_fma_f32 v184, v169, v169, v184
	v_cvt_pk_bf16_f32 v38, v168, v169
	v_lshlrev_b32_e32 v168, 16, v39
	v_and_b32_e32 v169, 0xffff0000, v39
	v_lshlrev_b32_e32 v170, 16, v71
	v_and_b32_e32 v171, 0xffff0000, v71
	v_mul_f32_e32 v170, s3, v170
	v_mul_f32_e32 v171, s3, v171
	v_fma_f32 v168, v170, v16, v168
	v_fma_f32 v169, v171, v17, v169
	v_fma_f32 v184, v168, v168, v184
	v_fma_f32 v184, v169, v169, v184
	v_cvt_pk_bf16_f32 v39, v168, v169
	global_store_dwordx4 v18, v[32:35], s[0:1]
	global_store_dwordx4 v18, v[36:39], s[0:1] offset:1024
	v_lshlrev_b32_e32 v168, 16, v40
	v_and_b32_e32 v169, 0xffff0000, v40
	v_lshlrev_b32_e32 v170, 16, v72
	v_and_b32_e32 v171, 0xffff0000, v72
	v_mul_f32_e32 v170, s24, v170
	v_mul_f32_e32 v171, s24, v171
	v_fma_f32 v168, v170, v2, v168
	v_fma_f32 v169, v171, v3, v169
	v_fma_f32 v185, v168, v168, v185
	v_fma_f32 v185, v169, v169, v185
	v_cvt_pk_bf16_f32 v40, v168, v169
	v_lshlrev_b32_e32 v168, 16, v41
	v_and_b32_e32 v169, 0xffff0000, v41
	v_lshlrev_b32_e32 v170, 16, v73
	v_and_b32_e32 v171, 0xffff0000, v73
	v_mul_f32_e32 v170, s24, v170
	v_mul_f32_e32 v171, s24, v171
	v_fma_f32 v168, v170, v4, v168
	v_fma_f32 v169, v171, v5, v169
	v_fma_f32 v185, v168, v168, v185
	v_fma_f32 v185, v169, v169, v185
	v_cvt_pk_bf16_f32 v41, v168, v169
	v_lshlrev_b32_e32 v168, 16, v42
	v_and_b32_e32 v169, 0xffff0000, v42
	v_lshlrev_b32_e32 v170, 16, v74
	v_and_b32_e32 v171, 0xffff0000, v74
	v_mul_f32_e32 v170, s24, v170
	v_mul_f32_e32 v171, s24, v171
	v_fma_f32 v168, v170, v6, v168
	v_fma_f32 v169, v171, v7, v169
	v_fma_f32 v185, v168, v168, v185
	v_fma_f32 v185, v169, v169, v185
	v_cvt_pk_bf16_f32 v42, v168, v169
	v_lshlrev_b32_e32 v168, 16, v43
	v_and_b32_e32 v169, 0xffff0000, v43
	v_lshlrev_b32_e32 v170, 16, v75
	v_and_b32_e32 v171, 0xffff0000, v75
	v_mul_f32_e32 v170, s24, v170
	v_mul_f32_e32 v171, s24, v171
	v_fma_f32 v168, v170, v8, v168
	v_fma_f32 v169, v171, v9, v169
	v_fma_f32 v185, v168, v168, v185
	v_fma_f32 v185, v169, v169, v185
	v_cvt_pk_bf16_f32 v43, v168, v169
	v_lshlrev_b32_e32 v168, 16, v44
	v_and_b32_e32 v169, 0xffff0000, v44
	v_lshlrev_b32_e32 v170, 16, v76
	v_and_b32_e32 v171, 0xffff0000, v76
	v_mul_f32_e32 v170, s24, v170
	v_mul_f32_e32 v171, s24, v171
	v_fma_f32 v168, v170, v10, v168
	v_fma_f32 v169, v171, v11, v169
	v_fma_f32 v185, v168, v168, v185
	v_fma_f32 v185, v169, v169, v185
	v_cvt_pk_bf16_f32 v44, v168, v169
	v_lshlrev_b32_e32 v168, 16, v45
	v_and_b32_e32 v169, 0xffff0000, v45
	v_lshlrev_b32_e32 v170, 16, v77
	v_and_b32_e32 v171, 0xffff0000, v77
	v_mul_f32_e32 v170, s24, v170
	v_mul_f32_e32 v171, s24, v171
	v_fma_f32 v168, v170, v12, v168
	v_fma_f32 v169, v171, v13, v169
	v_fma_f32 v185, v168, v168, v185
	v_fma_f32 v185, v169, v169, v185
	v_cvt_pk_bf16_f32 v45, v168, v169
	v_lshlrev_b32_e32 v168, 16, v46
	v_and_b32_e32 v169, 0xffff0000, v46
	v_lshlrev_b32_e32 v170, 16, v78
	v_and_b32_e32 v171, 0xffff0000, v78
	v_mul_f32_e32 v170, s24, v170
	v_mul_f32_e32 v171, s24, v171
	v_fma_f32 v168, v170, v14, v168
	v_fma_f32 v169, v171, v15, v169
	v_fma_f32 v185, v168, v168, v185
	v_fma_f32 v185, v169, v169, v185
	v_cvt_pk_bf16_f32 v46, v168, v169
	v_lshlrev_b32_e32 v168, 16, v47
	v_and_b32_e32 v169, 0xffff0000, v47
	v_lshlrev_b32_e32 v170, 16, v79
	v_and_b32_e32 v171, 0xffff0000, v79
	v_mul_f32_e32 v170, s24, v170
	v_mul_f32_e32 v171, s24, v171
	v_fma_f32 v168, v170, v16, v168
	v_fma_f32 v169, v171, v17, v169
	v_fma_f32 v185, v168, v168, v185
	v_fma_f32 v185, v169, v169, v185
	v_cvt_pk_bf16_f32 v47, v168, v169
	global_store_dwordx4 v18, v[40:43], s[0:1] offset:2048
	global_store_dwordx4 v18, v[44:47], s[0:1] offset:3072
	v_lshlrev_b32_e32 v168, 16, v48
	v_and_b32_e32 v169, 0xffff0000, v48
	v_lshlrev_b32_e32 v170, 16, v80
	v_and_b32_e32 v171, 0xffff0000, v80
	v_mul_f32_e32 v170, s98, v170
	v_mul_f32_e32 v171, s98, v171
	v_fma_f32 v168, v170, v2, v168
	v_fma_f32 v169, v171, v3, v169
	v_fma_f32 v186, v168, v168, v186
	v_fma_f32 v186, v169, v169, v186
	v_cvt_pk_bf16_f32 v48, v168, v169
	v_lshlrev_b32_e32 v168, 16, v49
	v_and_b32_e32 v169, 0xffff0000, v49
	v_lshlrev_b32_e32 v170, 16, v81
	v_and_b32_e32 v171, 0xffff0000, v81
	v_mul_f32_e32 v170, s98, v170
	v_mul_f32_e32 v171, s98, v171
	v_fma_f32 v168, v170, v4, v168
	v_fma_f32 v169, v171, v5, v169
	v_fma_f32 v186, v168, v168, v186
	v_fma_f32 v186, v169, v169, v186
	v_cvt_pk_bf16_f32 v49, v168, v169
	v_lshlrev_b32_e32 v168, 16, v50
	v_and_b32_e32 v169, 0xffff0000, v50
	v_lshlrev_b32_e32 v170, 16, v82
	v_and_b32_e32 v171, 0xffff0000, v82
	v_mul_f32_e32 v170, s98, v170
	v_mul_f32_e32 v171, s98, v171
	v_fma_f32 v168, v170, v6, v168
	v_fma_f32 v169, v171, v7, v169
	v_fma_f32 v186, v168, v168, v186
	v_fma_f32 v186, v169, v169, v186
	v_cvt_pk_bf16_f32 v50, v168, v169
	v_lshlrev_b32_e32 v168, 16, v51
	v_and_b32_e32 v169, 0xffff0000, v51
; __device__ __forceinline__ float bf_lo(unsigned w) { return __uint_as_float(w << 16); }
; __device__ __forceinline__ float bf_hi(unsigned w) { return __uint_as_float(w & 0xffff0000u); }
; __device__ __forceinline__ unsigned pk2(float lo, float hi) { bf16x2_t r = __builtin_convertvector((f32x2_t){lo, hi}, bf16x2_t); return __builtin_bit_cast(unsigned, r); }
; template <bool SRC_F32, bool FINAL, int R> __device__ __forceinline__ void ew_compute(const EwSet<SRC_F32, R>& S, int rb, const f32x4 (&g)[4], bf16* hb_out, float* out32, float scale, float* rs_out, int lane) {
;     ...
; #pragma unroll
;         for (int j = 0; j < 4; ++j) {
;             f32x4 h;
;             if constexpr (SRC_F32) h = S.h32[i][j];
;             else { const v2u hw = S.hb[i][j]; h.x = bf_lo(hw.x); h.y = bf_hi(hw.x); h.z = bf_lo(hw.y); h.w = bf_hi(hw.y); }
;             const v2u fw = S.fw[i][j];
;             f32x4 v; v.x = h.x + bf_lo(fw.x) * rs * g[j].x; v.y = h.y + bf_hi(fw.x) * rs * g[j].y; v.z = h.z + bf_lo(fw.y) * rs * g[j].z; v.w = h.w + bf_hi(fw.y) * rs * g[j].w;
;             if (FINAL) __builtin_nontemporal_store(v, (f32x4*)(out32 + (size_t)(rb + i) * D) + lane + 64 * j);
;             else { v2u o; o.x = pk2(v.x, v.y); o.y = pk2(v.z, v.w); ((v2u*)(hb_out + (size_t)(rb + i) * D) + lane)[64 * j] = o; s2 += (v.x * v.x + v.y * v.y) + (v.z * v.z + v.w * v.w); }
;         }
;         if (!FINAL) { const float tot = wave_sum(s2); if (lane == 0) rs_out[rb + i] = 1.0f / sqrtf(tot * (1.f / D) + EPS); }
	v_lshlrev_b32_e32 v170, 16, v83
	v_and_b32_e32 v171, 0xffff0000, v83
	v_mul_f32_e32 v170, s98, v170
	v_mul_f32_e32 v171, s98, v171
	v_fma_f32 v168, v170, v8, v168
	v_fma_f32 v169, v171, v9, v169
	v_fma_f32 v186, v168, v168, v186
	v_fma_f32 v186, v169, v169, v186
	v_cvt_pk_bf16_f32 v51, v168, v169
	v_lshlrev_b32_e32 v168, 16, v52
	v_and_b32_e32 v169, 0xffff0000, v52
	v_lshlrev_b32_e32 v170, 16, v84
	v_and_b32_e32 v171, 0xffff0000, v84
	v_mul_f32_e32 v170, s98, v170
	v_mul_f32_e32 v171, s98, v171
	v_fma_f32 v168, v170, v10, v168
	v_fma_f32 v169, v171, v11, v169
	v_fma_f32 v186, v168, v168, v186
	v_fma_f32 v186, v169, v169, v186
	v_cvt_pk_bf16_f32 v52, v168, v169
	v_lshlrev_b32_e32 v168, 16, v53
	v_and_b32_e32 v169, 0xffff0000, v53
	v_lshlrev_b32_e32 v170, 16, v85
	v_and_b32_e32 v171, 0xffff0000, v85
	v_mul_f32_e32 v170, s98, v170
	v_mul_f32_e32 v171, s98, v171
	v_fma_f32 v168, v170, v12, v168
	v_fma_f32 v169, v171, v13, v169
	v_fma_f32 v186, v168, v168, v186
	v_fma_f32 v186, v169, v169, v186
	v_cvt_pk_bf16_f32 v53, v168, v169
	v_lshlrev_b32_e32 v168, 16, v54
	v_and_b32_e32 v169, 0xffff0000, v54
	v_lshlrev_b32_e32 v170, 16, v86
	v_and_b32_e32 v171, 0xffff0000, v86
	v_mul_f32_e32 v170, s98, v170
	v_mul_f32_e32 v171, s98, v171
	v_fma_f32 v168, v170, v14, v168
	v_fma_f32 v169, v171, v15, v169
	v_fma_f32 v186, v168, v168, v186
	v_fma_f32 v186, v169, v169, v186
	v_cvt_pk_bf16_f32 v54, v168, v169
	v_lshlrev_b32_e32 v168, 16, v55
	v_and_b32_e32 v169, 0xffff0000, v55
	v_lshlrev_b32_e32 v170, 16, v87
	v_and_b32_e32 v171, 0xffff0000, v87
	v_mul_f32_e32 v170, s98, v170
	v_mul_f32_e32 v171, s98, v171
	v_fma_f32 v168, v170, v16, v168
	v_fma_f32 v169, v171, v17, v169
	v_fma_f32 v186, v168, v168, v186
	v_fma_f32 v186, v169, v169, v186
	v_cvt_pk_bf16_f32 v55, v168, v169
	global_store_dwordx4 v19, v[48:51], s[0:1]
	global_store_dwordx4 v19, v[52:55], s[0:1] offset:1024
	v_lshlrev_b32_e32 v168, 16, v56
	v_and_b32_e32 v169, 0xffff0000, v56
	v_lshlrev_b32_e32 v170, 16, v88
	v_and_b32_e32 v171, 0xffff0000, v88
	v_mul_f32_e32 v170, s101, v170
	v_mul_f32_e32 v171, s101, v171
	v_fma_f32 v168, v170, v2, v168
	v_fma_f32 v169, v171, v3, v169
	v_fma_f32 v187, v168, v168, v187
	v_fma_f32 v187, v169, v169, v187
	v_cvt_pk_bf16_f32 v56, v168, v169
	v_lshlrev_b32_e32 v168, 16, v57
	v_and_b32_e32 v169, 0xffff0000, v57
	v_lshlrev_b32_e32 v170, 16, v89
	v_and_b32_e32 v171, 0xffff0000, v89
	v_mul_f32_e32 v170, s101, v170
	v_mul_f32_e32 v171, s101, v171
	v_fma_f32 v168, v170, v4, v168
	v_fma_f32 v169, v171, v5, v169
	v_fma_f32 v187, v168, v168, v187
	v_fma_f32 v187, v169, v169, v187
	v_cvt_pk_bf16_f32 v57, v168, v169
	v_lshlrev_b32_e32 v168, 16, v58
	v_and_b32_e32 v169, 0xffff0000, v58
	v_lshlrev_b32_e32 v170, 16, v90
	v_and_b32_e32 v171, 0xffff0000, v90
	v_mul_f32_e32 v170, s101, v170
	v_mul_f32_e32 v171, s101, v171
	v_fma_f32 v168, v170, v6, v168
	v_fma_f32 v169, v171, v7, v169
	v_fma_f32 v187, v168, v168, v187
	v_fma_f32 v187, v169, v169, v187
	v_cvt_pk_bf16_f32 v58, v168, v169
	v_lshlrev_b32_e32 v168, 16, v59
	v_and_b32_e32 v169, 0xffff0000, v59
	v_lshlrev_b32_e32 v170, 16, v91
	v_and_b32_e32 v171, 0xffff0000, v91
	v_mul_f32_e32 v170, s101, v170
	v_mul_f32_e32 v171, s101, v171
	v_fma_f32 v168, v170, v8, v168
	v_fma_f32 v169, v171, v9, v169
	v_fma_f32 v187, v168, v168, v187
	v_fma_f32 v187, v169, v169, v187
	v_cvt_pk_bf16_f32 v59, v168, v169
	v_lshlrev_b32_e32 v168, 16, v60
	v_and_b32_e32 v169, 0xffff0000, v60
	v_lshlrev_b32_e32 v170, 16, v92
	v_and_b32_e32 v171, 0xffff0000, v92
	v_mul_f32_e32 v170, s101, v170
	v_mul_f32_e32 v171, s101, v171
	v_fma_f32 v168, v170, v10, v168
	v_fma_f32 v169, v171, v11, v169
	v_fma_f32 v187, v168, v168, v187
	v_fma_f32 v187, v169, v169, v187
	v_cvt_pk_bf16_f32 v60, v168, v169
	v_lshlrev_b32_e32 v168, 16, v61
	v_and_b32_e32 v169, 0xffff0000, v61
	v_lshlrev_b32_e32 v170, 16, v93
	v_and_b32_e32 v171, 0xffff0000, v93
	v_mul_f32_e32 v170, s101, v170
	v_mul_f32_e32 v171, s101, v171
	v_fma_f32 v168, v170, v12, v168
	v_fma_f32 v169, v171, v13, v169
	v_fma_f32 v187, v168, v168, v187
	v_fma_f32 v187, v169, v169, v187
	v_cvt_pk_bf16_f32 v61, v168, v169
	v_lshlrev_b32_e32 v168, 16, v62
	v_and_b32_e32 v169, 0xffff0000, v62
	v_lshlrev_b32_e32 v170, 16, v94
	v_and_b32_e32 v171, 0xffff0000, v94
	v_mul_f32_e32 v170, s101, v170
	v_mul_f32_e32 v171, s101, v171
	v_fma_f32 v168, v170, v14, v168
	v_fma_f32 v169, v171, v15, v169
	v_fma_f32 v187, v168, v168, v187
	v_fma_f32 v187, v169, v169, v187
	v_cvt_pk_bf16_f32 v62, v168, v169
	v_lshlrev_b32_e32 v168, 16, v63
	v_and_b32_e32 v169, 0xffff0000, v63
	v_lshlrev_b32_e32 v170, 16, v95
	v_and_b32_e32 v171, 0xffff0000, v95
	v_mul_f32_e32 v170, s101, v170
	v_mul_f32_e32 v171, s101, v171
	v_fma_f32 v168, v170, v16, v168
	v_fma_f32 v169, v171, v17, v169
	v_fma_f32 v187, v168, v168, v187
	v_fma_f32 v187, v169, v169, v187
	v_cvt_pk_bf16_f32 v63, v168, v169
	global_store_dwordx4 v19, v[56:59], s[0:1] offset:2048
	global_store_dwordx4 v19, v[60:63], s[0:1] offset:3072
	s_nop 1
	v_add_f32_dpp v184, v184, v184 quad_perm:[1,0,3,2] row_mask:0xf bank_mask:0xf
	v_add_f32_dpp v185, v185, v185 quad_perm:[1,0,3,2] row_mask:0xf bank_mask:0xf
	v_add_f32_dpp v186, v186, v186 quad_perm:[1,0,3,2] row_mask:0xf bank_mask:0xf
	v_add_f32_dpp v187, v187, v187 quad_perm:[1,0,3,2] row_mask:0xf bank_mask:0xf
	v_add_f32_dpp v184, v184, v184 quad_perm:[2,3,0,1] row_mask:0xf bank_mask:0xf
	v_add_f32_dpp v185, v185, v185 quad_perm:[2,3,0,1] row_mask:0xf bank_mask:0xf
	v_add_f32_dpp v186, v186, v186 quad_perm:[2,3,0,1] row_mask:0xf bank_mask:0xf
	v_add_f32_dpp v187, v187, v187 quad_perm:[2,3,0,1] row_mask:0xf bank_mask:0xf
; __device__ __forceinline__ float bf_lo(unsigned w) { return __uint_as_float(w << 16); }
; __device__ __forceinline__ float bf_hi(unsigned w) { return __uint_as_float(w & 0xffff0000u); }
; __device__ __forceinline__ unsigned pk2(float lo, float hi) { bf16x2_t r = __builtin_convertvector((f32x2_t){lo, hi}, bf16x2_t); return __builtin_bit_cast(unsigned, r); }
; template <bool SRC_F32, bool FINAL, int R> __device__ __forceinline__ void ew_compute(const EwSet<SRC_F32, R>& S, int rb, const f32x4 (&g)[4], bf16* hb_out, float* out32, float scale, float* rs_out, int lane) {
;     ...
; #pragma unroll
;         for (int j = 0; j < 4; ++j) {
;             f32x4 h;
;             if constexpr (SRC_F32) h = S.h32[i][j];
;             else { const v2u hw = S.hb[i][j]; h.x = bf_lo(hw.x); h.y = bf_hi(hw.x); h.z = bf_lo(hw.y); h.w = bf_hi(hw.y); }
;             const v2u fw = S.fw[i][j];
;             f32x4 v; v.x = h.x + bf_lo(fw.x) * rs * g[j].x; v.y = h.y + bf_hi(fw.x) * rs * g[j].y; v.z = h.z + bf_lo(fw.y) * rs * g[j].z; v.w = h.w + bf_hi(fw.y) * rs * g[j].w;
;             if (FINAL) __builtin_nontemporal_store(v, (f32x4*)(out32 + (size_t)(rb + i) * D) + lane + 64 * j);
;             else { v2u o; o.x = pk2(v.x, v.y); o.y = pk2(v.z, v.w); ((v2u*)(hb_out + (size_t)(rb + i) * D) + lane)[64 * j] = o; s2 += (v.x * v.x + v.y * v.y) + (v.z * v.z + v.w * v.w); }
;         }
;         if (!FINAL) { const float tot = wave_sum(s2); if (lane == 0) rs_out[rb + i] = 1.0f / sqrtf(tot * (1.f / D) + EPS); }
	v_add_f32_dpp v184, v184, v184 row_half_mirror row_mask:0xf bank_mask:0xf
	v_add_f32_dpp v185, v185, v185 row_half_mirror row_mask:0xf bank_mask:0xf
	v_add_f32_dpp v186, v186, v186 row_half_mirror row_mask:0xf bank_mask:0xf
	v_add_f32_dpp v187, v187, v187 row_half_mirror row_mask:0xf bank_mask:0xf
	v_add_f32_dpp v184, v184, v184 row_mirror row_mask:0xf bank_mask:0xf
	v_add_f32_dpp v185, v185, v185 row_mirror row_mask:0xf bank_mask:0xf
	v_add_f32_dpp v186, v186, v186 row_mirror row_mask:0xf bank_mask:0xf
	v_add_f32_dpp v187, v187, v187 row_mirror row_mask:0xf bank_mask:0xf
	v_add_f32_dpp v184, v184, v184 row_bcast:15 row_mask:0xa bank_mask:0xf
	v_add_f32_dpp v185, v185, v185 row_bcast:15 row_mask:0xa bank_mask:0xf
	v_add_f32_dpp v186, v186, v186 row_bcast:15 row_mask:0xa bank_mask:0xf
	v_add_f32_dpp v187, v187, v187 row_bcast:15 row_mask:0xa bank_mask:0xf
	v_add_f32_dpp v184, v184, v184 row_bcast:31 row_mask:0xc bank_mask:0xf
	v_add_f32_dpp v185, v185, v185 row_bcast:31 row_mask:0xc bank_mask:0xf
	v_add_f32_dpp v186, v186, v186 row_bcast:31 row_mask:0xc bank_mask:0xf
	v_add_f32_dpp v187, v187, v187 row_bcast:31 row_mask:0xc bank_mask:0xf
	s_nop 1
	v_readlane_b32 s3, v184, 63
	v_readlane_b32 s24, v185, 63
	v_readlane_b32 s98, v186, 63
	v_readlane_b32 s101, v187, 63
	s_nop 3
	v_writelane_b32 v188, s3, 0
	v_writelane_b32 v188, s24, 1
	v_writelane_b32 v188, s98, 2
	v_writelane_b32 v188, s101, 3
	s_nop 1
	v_mul_f32_e32 v188, 0x3a800000, v188
	v_add_f32_e32 v188, 0x358637bd, v188
	v_rsq_f32_e32 v188, v188
	s_mov_b64 exec, 15
	global_store_dword v21, v188, s[14:15]
	s_mov_b64 exec, -1
	s_add_u32 s27, s26, 2048
	s_lshl_b32 s22, s27, 11
	v_lshl_add_u32 v18, v0, 4, s22
	v_add_u32_e32 v19, 0x1000, v18
	s_lshl_b32 s22, s27, 6
	v_lshl_add_u32 v20, v0, 2, s22
	s_lshl_b32 s22, s27, 2
	v_lshl_add_u32 v21, v0, 2, s22
	global_load_dwordx4 v[32:35], v18, s[0:1]
	global_load_dwordx4 v[36:39], v18, s[0:1] offset:1024
	global_load_dwordx4 v[64:67], v18, s[4:5]
	global_load_dwordx4 v[68:71], v18, s[4:5] offset:1024
	global_load_dwordx4 v[40:43], v18, s[0:1] offset:2048
	global_load_dwordx4 v[44:47], v18, s[0:1] offset:3072
	global_load_dwordx4 v[72:75], v18, s[4:5] offset:2048
	global_load_dwordx4 v[76:79], v18, s[4:5] offset:3072
	global_load_dwordx4 v[48:51], v19, s[0:1]
	global_load_dwordx4 v[52:55], v19, s[0:1] offset:1024
	global_load_dwordx4 v[80:83], v19, s[4:5]
	global_load_dwordx4 v[84:87], v19, s[4:5] offset:1024
	global_load_dwordx4 v[56:59], v19, s[0:1] offset:2048
	global_load_dwordx4 v[60:63], v19, s[0:1] offset:3072
	global_load_dwordx4 v[88:91], v19, s[4:5] offset:2048
	global_load_dwordx4 v[92:95], v19, s[4:5] offset:3072
	global_load_dword v96, v20, s[6:7]
	s_waitcnt vmcnt(26)
	v_add_f32_dpp v164, v164, v164 quad_perm:[1,0,3,2] row_mask:0xf bank_mask:0xf
	s_nop 1
	v_add_f32_dpp v164, v164, v164 quad_perm:[2,3,0,1] row_mask:0xf bank_mask:0xf
	s_nop 1
	v_add_f32_dpp v164, v164, v164 row_half_mirror row_mask:0xf bank_mask:0xf
	s_nop 1
	v_add_f32_dpp v164, v164, v164 row_mirror row_mask:0xf bank_mask:0xf
	s_nop 1
	v_mul_f32_e32 v164, 0x3a800000, v164
	v_add_f32_e32 v164, 0x358637bd, v164
	v_rsq_f32_e32 v164, v164
	s_nop 0
	v_readlane_b32 s3, v164, 0
	v_readlane_b32 s24, v164, 16
	v_readlane_b32 s98, v164, 32
	v_readlane_b32 s101, v164, 48
	s_nop 1
	v_mov_b32_e32 v184, 0
	v_mov_b32_e32 v185, 0
	v_mov_b32_e32 v186, 0
	v_mov_b32_e32 v187, 0
	v_lshlrev_b32_e32 v168, 16, v100
	v_and_b32_e32 v169, 0xffff0000, v100
	v_lshlrev_b32_e32 v170, 16, v132
	v_and_b32_e32 v171, 0xffff0000, v132
	v_mul_f32_e32 v170, s3, v170
	v_mul_f32_e32 v171, s3, v171
	v_fma_f32 v168, v170, v2, v168
	v_fma_f32 v169, v171, v3, v169
	v_fma_f32 v184, v168, v168, v184
	v_fma_f32 v184, v169, v169, v184
	v_cvt_pk_bf16_f32 v100, v168, v169
	v_lshlrev_b32_e32 v168, 16, v101
	v_and_b32_e32 v169, 0xffff0000, v101
	v_lshlrev_b32_e32 v170, 16, v133
	v_and_b32_e32 v171, 0xffff0000, v133
	v_mul_f32_e32 v170, s3, v170
	v_mul_f32_e32 v171, s3, v171
	v_fma_f32 v168, v170, v4, v168
	v_fma_f32 v169, v171, v5, v169
	v_fma_f32 v184, v168, v168, v184
	v_fma_f32 v184, v169, v169, v184
	v_cvt_pk_bf16_f32 v101, v168, v169
	v_lshlrev_b32_e32 v168, 16, v102
	v_and_b32_e32 v169, 0xffff0000, v102
	v_lshlrev_b32_e32 v170, 16, v134
	v_and_b32_e32 v171, 0xffff0000, v134
	v_mul_f32_e32 v170, s3, v170
	v_mul_f32_e32 v171, s3, v171
	v_fma_f32 v168, v170, v6, v168
	v_fma_f32 v169, v171, v7, v169
	v_fma_f32 v184, v168, v168, v184
	v_fma_f32 v184, v169, v169, v184
	v_cvt_pk_bf16_f32 v102, v168, v169
	v_lshlrev_b32_e32 v168, 16, v103
	v_and_b32_e32 v169, 0xffff0000, v103
	v_lshlrev_b32_e32 v170, 16, v135
	v_and_b32_e32 v171, 0xffff0000, v135
	v_mul_f32_e32 v170, s3, v170
	v_mul_f32_e32 v171, s3, v171
	v_fma_f32 v168, v170, v8, v168
	v_fma_f32 v169, v171, v9, v169
	v_fma_f32 v184, v168, v168, v184
	v_fma_f32 v184, v169, v169, v184
	v_cvt_pk_bf16_f32 v103, v168, v169
	v_lshlrev_b32_e32 v168, 16, v104
	v_and_b32_e32 v169, 0xffff0000, v104
	v_lshlrev_b32_e32 v170, 16, v136
	v_and_b32_e32 v171, 0xffff0000, v136
	v_mul_f32_e32 v170, s3, v170
	v_mul_f32_e32 v171, s3, v171
	v_fma_f32 v168, v170, v10, v168
	v_fma_f32 v169, v171, v11, v169
	v_fma_f32 v184, v168, v168, v184
	v_fma_f32 v184, v169, v169, v184
	v_cvt_pk_bf16_f32 v104, v168, v169
	v_lshlrev_b32_e32 v168, 16, v105
	v_and_b32_e32 v169, 0xffff0000, v105
	v_lshlrev_b32_e32 v170, 16, v137
	v_and_b32_e32 v171, 0xffff0000, v137
	v_mul_f32_e32 v170, s3, v170
	v_mul_f32_e32 v171, s3, v171
	v_fma_f32 v168, v170, v12, v168
	v_fma_f32 v169, v171, v13, v169
	v_fma_f32 v184, v168, v168, v184
	v_fma_f32 v184, v169, v169, v184
	v_cvt_pk_bf16_f32 v105, v168, v169
; __device__ __forceinline__ float bf_lo(unsigned w) { return __uint_as_float(w << 16); }
; __device__ __forceinline__ float bf_hi(unsigned w) { return __uint_as_float(w & 0xffff0000u); }
; __device__ __forceinline__ unsigned pk2(float lo, float hi) { bf16x2_t r = __builtin_convertvector((f32x2_t){lo, hi}, bf16x2_t); return __builtin_bit_cast(unsigned, r); }
; template <bool SRC_F32, bool FINAL, int R> __device__ __forceinline__ void ew_compute(const EwSet<SRC_F32, R>& S, int rb, const f32x4 (&g)[4], bf16* hb_out, float* out32, float scale, float* rs_out, int lane) {
;     ...
; #pragma unroll
;         for (int j = 0; j < 4; ++j) {
;             f32x4 h;
;             if constexpr (SRC_F32) h = S.h32[i][j];
;             else { const v2u hw = S.hb[i][j]; h.x = bf_lo(hw.x); h.y = bf_hi(hw.x); h.z = bf_lo(hw.y); h.w = bf_hi(hw.y); }
;             const v2u fw = S.fw[i][j];
;             f32x4 v; v.x = h.x + bf_lo(fw.x) * rs * g[j].x; v.y = h.y + bf_hi(fw.x) * rs * g[j].y; v.z = h.z + bf_lo(fw.y) * rs * g[j].z; v.w = h.w + bf_hi(fw.y) * rs * g[j].w;
;             if (FINAL) __builtin_nontemporal_store(v, (f32x4*)(out32 + (size_t)(rb + i) * D) + lane + 64 * j);
;             else { v2u o; o.x = pk2(v.x, v.y); o.y = pk2(v.z, v.w); ((v2u*)(hb_out + (size_t)(rb + i) * D) + lane)[64 * j] = o; s2 += (v.x * v.x + v.y * v.y) + (v.z * v.z + v.w * v.w); }
;         }
;         if (!FINAL) { const float tot = wave_sum(s2); if (lane == 0) rs_out[rb + i] = 1.0f / sqrtf(tot * (1.f / D) + EPS); }
	v_lshlrev_b32_e32 v168, 16, v106
	v_and_b32_e32 v169, 0xffff0000, v106
	v_lshlrev_b32_e32 v170, 16, v138
	v_and_b32_e32 v171, 0xffff0000, v138
	v_mul_f32_e32 v170, s3, v170
	v_mul_f32_e32 v171, s3, v171
	v_fma_f32 v168, v170, v14, v168
	v_fma_f32 v169, v171, v15, v169
	v_fma_f32 v184, v168, v168, v184
	v_fma_f32 v184, v169, v169, v184
	v_cvt_pk_bf16_f32 v106, v168, v169
	v_lshlrev_b32_e32 v168, 16, v107
	v_and_b32_e32 v169, 0xffff0000, v107
	v_lshlrev_b32_e32 v170, 16, v139
	v_and_b32_e32 v171, 0xffff0000, v139
	v_mul_f32_e32 v170, s3, v170
	v_mul_f32_e32 v171, s3, v171
	v_fma_f32 v168, v170, v16, v168
	v_fma_f32 v169, v171, v17, v169
	v_fma_f32 v184, v168, v168, v184
	v_fma_f32 v184, v169, v169, v184
	v_cvt_pk_bf16_f32 v107, v168, v169
	global_store_dwordx4 v23, v[100:103], s[0:1]
	global_store_dwordx4 v23, v[104:107], s[0:1] offset:1024
	v_lshlrev_b32_e32 v168, 16, v108
	v_and_b32_e32 v169, 0xffff0000, v108
	v_lshlrev_b32_e32 v170, 16, v140
	v_and_b32_e32 v171, 0xffff0000, v140
	v_mul_f32_e32 v170, s24, v170
	v_mul_f32_e32 v171, s24, v171
	v_fma_f32 v168, v170, v2, v168
	v_fma_f32 v169, v171, v3, v169
	v_fma_f32 v185, v168, v168, v185
	v_fma_f32 v185, v169, v169, v185
	v_cvt_pk_bf16_f32 v108, v168, v169
	v_lshlrev_b32_e32 v168, 16, v109
	v_and_b32_e32 v169, 0xffff0000, v109
	v_lshlrev_b32_e32 v170, 16, v141
	v_and_b32_e32 v171, 0xffff0000, v141
	v_mul_f32_e32 v170, s24, v170
	v_mul_f32_e32 v171, s24, v171
	v_fma_f32 v168, v170, v4, v168
	v_fma_f32 v169, v171, v5, v169
	v_fma_f32 v185, v168, v168, v185
	v_fma_f32 v185, v169, v169, v185
	v_cvt_pk_bf16_f32 v109, v168, v169
	v_lshlrev_b32_e32 v168, 16, v110
	v_and_b32_e32 v169, 0xffff0000, v110
	v_lshlrev_b32_e32 v170, 16, v142
	v_and_b32_e32 v171, 0xffff0000, v142
	v_mul_f32_e32 v170, s24, v170
	v_mul_f32_e32 v171, s24, v171
	v_fma_f32 v168, v170, v6, v168
	v_fma_f32 v169, v171, v7, v169
	v_fma_f32 v185, v168, v168, v185
	v_fma_f32 v185, v169, v169, v185
	v_cvt_pk_bf16_f32 v110, v168, v169
	v_lshlrev_b32_e32 v168, 16, v111
	v_and_b32_e32 v169, 0xffff0000, v111
	v_lshlrev_b32_e32 v170, 16, v143
	v_and_b32_e32 v171, 0xffff0000, v143
	v_mul_f32_e32 v170, s24, v170
	v_mul_f32_e32 v171, s24, v171
	v_fma_f32 v168, v170, v8, v168
	v_fma_f32 v169, v171, v9, v169
	v_fma_f32 v185, v168, v168, v185
	v_fma_f32 v185, v169, v169, v185
	v_cvt_pk_bf16_f32 v111, v168, v169
	v_lshlrev_b32_e32 v168, 16, v112
	v_and_b32_e32 v169, 0xffff0000, v112
	v_lshlrev_b32_e32 v170, 16, v144
	v_and_b32_e32 v171, 0xffff0000, v144
	v_mul_f32_e32 v170, s24, v170
	v_mul_f32_e32 v171, s24, v171
	v_fma_f32 v168, v170, v10, v168
	v_fma_f32 v169, v171, v11, v169
	v_fma_f32 v185, v168, v168, v185
	v_fma_f32 v185, v169, v169, v185
	v_cvt_pk_bf16_f32 v112, v168, v169
	v_lshlrev_b32_e32 v168, 16, v113
	v_and_b32_e32 v169, 0xffff0000, v113
	v_lshlrev_b32_e32 v170, 16, v145
	v_and_b32_e32 v171, 0xffff0000, v145
	v_mul_f32_e32 v170, s24, v170
	v_mul_f32_e32 v171, s24, v171
	v_fma_f32 v168, v170, v12, v168
	v_fma_f32 v169, v171, v13, v169
	v_fma_f32 v185, v168, v168, v185
	v_fma_f32 v185, v169, v169, v185
	v_cvt_pk_bf16_f32 v113, v168, v169
	v_lshlrev_b32_e32 v168, 16, v114
	v_and_b32_e32 v169, 0xffff0000, v114
	v_lshlrev_b32_e32 v170, 16, v146
	v_and_b32_e32 v171, 0xffff0000, v146
	v_mul_f32_e32 v170, s24, v170
	v_mul_f32_e32 v171, s24, v171
	v_fma_f32 v168, v170, v14, v168
	v_fma_f32 v169, v171, v15, v169
	v_fma_f32 v185, v168, v168, v185
	v_fma_f32 v185, v169, v169, v185
	v_cvt_pk_bf16_f32 v114, v168, v169
	v_lshlrev_b32_e32 v168, 16, v115
	v_and_b32_e32 v169, 0xffff0000, v115
	v_lshlrev_b32_e32 v170, 16, v147
	v_and_b32_e32 v171, 0xffff0000, v147
	v_mul_f32_e32 v170, s24, v170
	v_mul_f32_e32 v171, s24, v171
	v_fma_f32 v168, v170, v16, v168
	v_fma_f32 v169, v171, v17, v169
	v_fma_f32 v185, v168, v168, v185
	v_fma_f32 v185, v169, v169, v185
	v_cvt_pk_bf16_f32 v115, v168, v169
	global_store_dwordx4 v23, v[108:111], s[0:1] offset:2048
	global_store_dwordx4 v23, v[112:115], s[0:1] offset:3072
	v_lshlrev_b32_e32 v168, 16, v116
	v_and_b32_e32 v169, 0xffff0000, v116
	v_lshlrev_b32_e32 v170, 16, v148
	v_and_b32_e32 v171, 0xffff0000, v148
	v_mul_f32_e32 v170, s98, v170
	v_mul_f32_e32 v171, s98, v171
	v_fma_f32 v168, v170, v2, v168
	v_fma_f32 v169, v171, v3, v169
	v_fma_f32 v186, v168, v168, v186
	v_fma_f32 v186, v169, v169, v186
	v_cvt_pk_bf16_f32 v116, v168, v169
	v_lshlrev_b32_e32 v168, 16, v117
	v_and_b32_e32 v169, 0xffff0000, v117
	v_lshlrev_b32_e32 v170, 16, v149
	v_and_b32_e32 v171, 0xffff0000, v149
	v_mul_f32_e32 v170, s98, v170
	v_mul_f32_e32 v171, s98, v171
	v_fma_f32 v168, v170, v4, v168
	v_fma_f32 v169, v171, v5, v169
	v_fma_f32 v186, v168, v168, v186
	v_fma_f32 v186, v169, v169, v186
	v_cvt_pk_bf16_f32 v117, v168, v169
	v_lshlrev_b32_e32 v168, 16, v118
	v_and_b32_e32 v169, 0xffff0000, v118
	v_lshlrev_b32_e32 v170, 16, v150
	v_and_b32_e32 v171, 0xffff0000, v150
	v_mul_f32_e32 v170, s98, v170
	v_mul_f32_e32 v171, s98, v171
	v_fma_f32 v168, v170, v6, v168
	v_fma_f32 v169, v171, v7, v169
	v_fma_f32 v186, v168, v168, v186
	v_fma_f32 v186, v169, v169, v186
	v_cvt_pk_bf16_f32 v118, v168, v169
	v_lshlrev_b32_e32 v168, 16, v119
	v_and_b32_e32 v169, 0xffff0000, v119
	v_lshlrev_b32_e32 v170, 16, v151
	v_and_b32_e32 v171, 0xffff0000, v151
	v_mul_f32_e32 v170, s98, v170
	v_mul_f32_e32 v171, s98, v171
	v_fma_f32 v168, v170, v8, v168
	v_fma_f32 v169, v171, v9, v169
	v_fma_f32 v186, v168, v168, v186
	v_fma_f32 v186, v169, v169, v186
	v_cvt_pk_bf16_f32 v119, v168, v169
	v_lshlrev_b32_e32 v168, 16, v120
	v_and_b32_e32 v169, 0xffff0000, v120
	v_lshlrev_b32_e32 v170, 16, v152
	v_and_b32_e32 v171, 0xffff0000, v152
	v_mul_f32_e32 v170, s98, v170
; __device__ __forceinline__ float bf_lo(unsigned w) { return __uint_as_float(w << 16); }
; __device__ __forceinline__ float bf_hi(unsigned w) { return __uint_as_float(w & 0xffff0000u); }
; __device__ __forceinline__ unsigned pk2(float lo, float hi) { bf16x2_t r = __builtin_convertvector((f32x2_t){lo, hi}, bf16x2_t); return __builtin_bit_cast(unsigned, r); }
; template <bool SRC_F32, bool FINAL, int R> __device__ __forceinline__ void ew_compute(const EwSet<SRC_F32, R>& S, int rb, const f32x4 (&g)[4], bf16* hb_out, float* out32, float scale, float* rs_out, int lane) {
; #pragma unroll
;     for (int i = 0; i < R; ++i) {
;         float q = S.p[i];
;         q += __shfl_xor(q, 1); q += __shfl_xor(q, 2); q += __shfl_xor(q, 4); q += __shfl_xor(q, 8);
;         const float ss = __shfl(q, 0);
;         const float rs = scale / sqrtf(ss * (1.f / D) + EPS);
;         float s2 = 0.f;
; #pragma unroll
;         for (int j = 0; j < 4; ++j) {
;             f32x4 h;
;             if constexpr (SRC_F32) h = S.h32[i][j];
;             else { const v2u hw = S.hb[i][j]; h.x = bf_lo(hw.x); h.y = bf_hi(hw.x); h.z = bf_lo(hw.y); h.w = bf_hi(hw.y); }
;             const v2u fw = S.fw[i][j];
;             f32x4 v; v.x = h.x + bf_lo(fw.x) * rs * g[j].x; v.y = h.y + bf_hi(fw.x) * rs * g[j].y; v.z = h.z + bf_lo(fw.y) * rs * g[j].z; v.w = h.w + bf_hi(fw.y) * rs * g[j].w;
;             if (FINAL) __builtin_nontemporal_store(v, (f32x4*)(out32 + (size_t)(rb + i) * D) + lane + 64 * j);
;             else { v2u o; o.x = pk2(v.x, v.y); o.y = pk2(v.z, v.w); ((v2u*)(hb_out + (size_t)(rb + i) * D) + lane)[64 * j] = o; s2 += (v.x * v.x + v.y * v.y) + (v.z * v.z + v.w * v.w); }
;         }
;         if (!FINAL) { const float tot = wave_sum(s2); if (lane == 0) rs_out[rb + i] = 1.0f / sqrtf(tot * (1.f / D) + EPS); }
;     }
; }
	v_mul_f32_e32 v171, s98, v171
	v_fma_f32 v168, v170, v10, v168
	v_fma_f32 v169, v171, v11, v169
	v_fma_f32 v186, v168, v168, v186
	v_fma_f32 v186, v169, v169, v186
	v_cvt_pk_bf16_f32 v120, v168, v169
	v_lshlrev_b32_e32 v168, 16, v121
	v_and_b32_e32 v169, 0xffff0000, v121
	v_lshlrev_b32_e32 v170, 16, v153
	v_and_b32_e32 v171, 0xffff0000, v153
	v_mul_f32_e32 v170, s98, v170
	v_mul_f32_e32 v171, s98, v171
	v_fma_f32 v168, v170, v12, v168
	v_fma_f32 v169, v171, v13, v169
	v_fma_f32 v186, v168, v168, v186
	v_fma_f32 v186, v169, v169, v186
	v_cvt_pk_bf16_f32 v121, v168, v169
	v_lshlrev_b32_e32 v168, 16, v122
	v_and_b32_e32 v169, 0xffff0000, v122
	v_lshlrev_b32_e32 v170, 16, v154
	v_and_b32_e32 v171, 0xffff0000, v154
	v_mul_f32_e32 v170, s98, v170
	v_mul_f32_e32 v171, s98, v171
	v_fma_f32 v168, v170, v14, v168
	v_fma_f32 v169, v171, v15, v169
	v_fma_f32 v186, v168, v168, v186
	v_fma_f32 v186, v169, v169, v186
	v_cvt_pk_bf16_f32 v122, v168, v169
	v_lshlrev_b32_e32 v168, 16, v123
	v_and_b32_e32 v169, 0xffff0000, v123
	v_lshlrev_b32_e32 v170, 16, v155
	v_and_b32_e32 v171, 0xffff0000, v155
	v_mul_f32_e32 v170, s98, v170
	v_mul_f32_e32 v171, s98, v171
	v_fma_f32 v168, v170, v16, v168
	v_fma_f32 v169, v171, v17, v169
	v_fma_f32 v186, v168, v168, v186
	v_fma_f32 v186, v169, v169, v186
	v_cvt_pk_bf16_f32 v123, v168, v169
	global_store_dwordx4 v24, v[116:119], s[0:1]
	global_store_dwordx4 v24, v[120:123], s[0:1] offset:1024
	v_lshlrev_b32_e32 v168, 16, v124
	v_and_b32_e32 v169, 0xffff0000, v124
	v_lshlrev_b32_e32 v170, 16, v156
	v_and_b32_e32 v171, 0xffff0000, v156
	v_mul_f32_e32 v170, s101, v170
	v_mul_f32_e32 v171, s101, v171
	v_fma_f32 v168, v170, v2, v168
	v_fma_f32 v169, v171, v3, v169
	v_fma_f32 v187, v168, v168, v187
	v_fma_f32 v187, v169, v169, v187
	v_cvt_pk_bf16_f32 v124, v168, v169
	v_lshlrev_b32_e32 v168, 16, v125
	v_and_b32_e32 v169, 0xffff0000, v125
	v_lshlrev_b32_e32 v170, 16, v157
	v_and_b32_e32 v171, 0xffff0000, v157
	v_mul_f32_e32 v170, s101, v170
	v_mul_f32_e32 v171, s101, v171
	v_fma_f32 v168, v170, v4, v168
	v_fma_f32 v169, v171, v5, v169
	v_fma_f32 v187, v168, v168, v187
	v_fma_f32 v187, v169, v169, v187
	v_cvt_pk_bf16_f32 v125, v168, v169
	v_lshlrev_b32_e32 v168, 16, v126
	v_and_b32_e32 v169, 0xffff0000, v126
	v_lshlrev_b32_e32 v170, 16, v158
	v_and_b32_e32 v171, 0xffff0000, v158
	v_mul_f32_e32 v170, s101, v170
	v_mul_f32_e32 v171, s101, v171
	v_fma_f32 v168, v170, v6, v168
	v_fma_f32 v169, v171, v7, v169
	v_fma_f32 v187, v168, v168, v187
	v_fma_f32 v187, v169, v169, v187
	v_cvt_pk_bf16_f32 v126, v168, v169
	v_lshlrev_b32_e32 v168, 16, v127
	v_and_b32_e32 v169, 0xffff0000, v127
	v_lshlrev_b32_e32 v170, 16, v159
	v_and_b32_e32 v171, 0xffff0000, v159
	v_mul_f32_e32 v170, s101, v170
	v_mul_f32_e32 v171, s101, v171
	v_fma_f32 v168, v170, v8, v168
	v_fma_f32 v169, v171, v9, v169
	v_fma_f32 v187, v168, v168, v187
	v_fma_f32 v187, v169, v169, v187
	v_cvt_pk_bf16_f32 v127, v168, v169
	v_lshlrev_b32_e32 v168, 16, v128
	v_and_b32_e32 v169, 0xffff0000, v128
	v_lshlrev_b32_e32 v170, 16, v160
	v_and_b32_e32 v171, 0xffff0000, v160
	v_mul_f32_e32 v170, s101, v170
	v_mul_f32_e32 v171, s101, v171
	v_fma_f32 v168, v170, v10, v168
	v_fma_f32 v169, v171, v11, v169
	v_fma_f32 v187, v168, v168, v187
	v_fma_f32 v187, v169, v169, v187
	v_cvt_pk_bf16_f32 v128, v168, v169
	v_lshlrev_b32_e32 v168, 16, v129
	v_and_b32_e32 v169, 0xffff0000, v129
	v_lshlrev_b32_e32 v170, 16, v161
	v_and_b32_e32 v171, 0xffff0000, v161
	v_mul_f32_e32 v170, s101, v170
	v_mul_f32_e32 v171, s101, v171
	v_fma_f32 v168, v170, v12, v168
	v_fma_f32 v169, v171, v13, v169
	v_fma_f32 v187, v168, v168, v187
	v_fma_f32 v187, v169, v169, v187
	v_cvt_pk_bf16_f32 v129, v168, v169
	v_lshlrev_b32_e32 v168, 16, v130
	v_and_b32_e32 v169, 0xffff0000, v130
	v_lshlrev_b32_e32 v170, 16, v162
	v_and_b32_e32 v171, 0xffff0000, v162
	v_mul_f32_e32 v170, s101, v170
	v_mul_f32_e32 v171, s101, v171
	v_fma_f32 v168, v170, v14, v168
	v_fma_f32 v169, v171, v15, v169
	v_fma_f32 v187, v168, v168, v187
	v_fma_f32 v187, v169, v169, v187
	v_cvt_pk_bf16_f32 v130, v168, v169
	v_lshlrev_b32_e32 v168, 16, v131
	v_and_b32_e32 v169, 0xffff0000, v131
	v_lshlrev_b32_e32 v170, 16, v163
	v_and_b32_e32 v171, 0xffff0000, v163
	v_mul_f32_e32 v170, s101, v170
	v_mul_f32_e32 v171, s101, v171
	v_fma_f32 v168, v170, v16, v168
	v_fma_f32 v169, v171, v17, v169
	v_fma_f32 v187, v168, v168, v187
	v_fma_f32 v187, v169, v169, v187
	v_cvt_pk_bf16_f32 v131, v168, v169
	global_store_dwordx4 v24, v[124:127], s[0:1] offset:2048
	global_store_dwordx4 v24, v[128:131], s[0:1] offset:3072
	s_nop 1
	v_add_f32_dpp v184, v184, v184 quad_perm:[1,0,3,2] row_mask:0xf bank_mask:0xf
	v_add_f32_dpp v185, v185, v185 quad_perm:[1,0,3,2] row_mask:0xf bank_mask:0xf
	v_add_f32_dpp v186, v186, v186 quad_perm:[1,0,3,2] row_mask:0xf bank_mask:0xf
	v_add_f32_dpp v187, v187, v187 quad_perm:[1,0,3,2] row_mask:0xf bank_mask:0xf
	v_add_f32_dpp v184, v184, v184 quad_perm:[2,3,0,1] row_mask:0xf bank_mask:0xf
	v_add_f32_dpp v185, v185, v185 quad_perm:[2,3,0,1] row_mask:0xf bank_mask:0xf
	v_add_f32_dpp v186, v186, v186 quad_perm:[2,3,0,1] row_mask:0xf bank_mask:0xf
	v_add_f32_dpp v187, v187, v187 quad_perm:[2,3,0,1] row_mask:0xf bank_mask:0xf
	v_add_f32_dpp v184, v184, v184 row_half_mirror row_mask:0xf bank_mask:0xf
	v_add_f32_dpp v185, v185, v185 row_half_mirror row_mask:0xf bank_mask:0xf
	v_add_f32_dpp v186, v186, v186 row_half_mirror row_mask:0xf bank_mask:0xf
	v_add_f32_dpp v187, v187, v187 row_half_mirror row_mask:0xf bank_mask:0xf
	v_add_f32_dpp v184, v184, v184 row_mirror row_mask:0xf bank_mask:0xf
	v_add_f32_dpp v185, v185, v185 row_mirror row_mask:0xf bank_mask:0xf
; __device__ __forceinline__ float bf_lo(unsigned w) { return __uint_as_float(w << 16); }
; __device__ __forceinline__ float bf_hi(unsigned w) { return __uint_as_float(w & 0xffff0000u); }
; template <bool SRC_F32, int R> __device__ __forceinline__ void ew_load(EwSet<SRC_F32, R>& S, int rb, const float* hsrc32, const bf16* hsrcb, const bf16* f, const float* part, int lane) {
; #pragma unroll
;     for (int i = 0; i < R; ++i) S.p[i] = (lane < 16) ? part[(size_t)(rb + i) * 16 + lane] : 0.f;
; #pragma unroll
;     for (int i = 0; i < R; ++i)
; #pragma unroll
;         for (int j = 0; j < 4; ++j) {
;             S.fw[i][j] = ((const v2u*)(f + (size_t)(rb + i) * D) + lane)[64 * j];
;             if constexpr (SRC_F32) S.h32[i][j] = __builtin_nontemporal_load((const f32x4*)(hsrc32 + (size_t)(rb + i) * D) + lane + 64 * j);
;             else S.hb[i][j] = ((const v2u*)(hsrcb + (size_t)(rb + i) * D) + lane)[64 * j];
;         }
; }
; template <bool SRC_F32, bool FINAL, int R> __device__ __forceinline__ void ew_compute(const EwSet<SRC_F32, R>& S, int rb, const f32x4 (&g)[4], bf16* hb_out, float* out32, float scale, float* rs_out, int lane) {
; #pragma unroll
;     for (int i = 0; i < R; ++i) {
;         float q = S.p[i];
;         q += __shfl_xor(q, 1); q += __shfl_xor(q, 2); q += __shfl_xor(q, 4); q += __shfl_xor(q, 8);
;         const float ss = __shfl(q, 0);
;         const float rs = scale / sqrtf(ss * (1.f / D) + EPS);
;         float s2 = 0.f;
; #pragma unroll
;         for (int j = 0; j < 4; ++j) {
;             f32x4 h;
;             if constexpr (SRC_F32) h = S.h32[i][j];
;             else { const v2u hw = S.hb[i][j]; h.x = bf_lo(hw.x); h.y = bf_hi(hw.x); h.z = bf_lo(hw.y); h.w = bf_hi(hw.y); }
;             const v2u fw = S.fw[i][j];
;             f32x4 v; v.x = h.x + bf_lo(fw.x) * rs * g[j].x; v.y = h.y + bf_hi(fw.x) * rs * g[j].y; v.z = h.z + bf_lo(fw.y) * rs * g[j].z; v.w = h.w + bf_hi(fw.y) * rs * g[j].w;
;             if (FINAL) __builtin_nontemporal_store(v, (f32x4*)(out32 + (size_t)(rb + i) * D) + lane + 64 * j);
;             else { v2u o; o.x = pk2(v.x, v.y); o.y = pk2(v.z, v.w); ((v2u*)(hb_out + (size_t)(rb + i) * D) + lane)[64 * j] = o; s2 += (v.x * v.x + v.y * v.y) + (v.z * v.z + v.w * v.w); }
;         }
;         if (!FINAL) { const float tot = wave_sum(s2); if (lane == 0) rs_out[rb + i] = 1.0f / sqrtf(tot * (1.f / D) + EPS); }
;     }
; }
	v_add_f32_dpp v186, v186, v186 row_mirror row_mask:0xf bank_mask:0xf
	v_add_f32_dpp v187, v187, v187 row_mirror row_mask:0xf bank_mask:0xf
	v_add_f32_dpp v184, v184, v184 row_bcast:15 row_mask:0xa bank_mask:0xf
	v_add_f32_dpp v185, v185, v185 row_bcast:15 row_mask:0xa bank_mask:0xf
	v_add_f32_dpp v186, v186, v186 row_bcast:15 row_mask:0xa bank_mask:0xf
	v_add_f32_dpp v187, v187, v187 row_bcast:15 row_mask:0xa bank_mask:0xf
	v_add_f32_dpp v184, v184, v184 row_bcast:31 row_mask:0xc bank_mask:0xf
	v_add_f32_dpp v185, v185, v185 row_bcast:31 row_mask:0xc bank_mask:0xf
	v_add_f32_dpp v186, v186, v186 row_bcast:31 row_mask:0xc bank_mask:0xf
	v_add_f32_dpp v187, v187, v187 row_bcast:31 row_mask:0xc bank_mask:0xf
	s_nop 1
	v_readlane_b32 s3, v184, 63
	v_readlane_b32 s24, v185, 63
	v_readlane_b32 s98, v186, 63
	v_readlane_b32 s101, v187, 63
	s_nop 3
	v_writelane_b32 v188, s3, 0
	v_writelane_b32 v188, s24, 1
	v_writelane_b32 v188, s98, 2
	v_writelane_b32 v188, s101, 3
	s_nop 1
	v_mul_f32_e32 v188, 0x3a800000, v188
	v_add_f32_e32 v188, 0x358637bd, v188
	v_rsq_f32_e32 v188, v188
	s_mov_b64 exec, 15
	global_store_dword v26, v188, s[14:15]
	s_mov_b64 exec, -1
	s_add_u32 s27, s26, 2052
	s_lshl_b32 s22, s27, 11
	v_lshl_add_u32 v23, v0, 4, s22
	v_add_u32_e32 v24, 0x1000, v23
	s_lshl_b32 s22, s27, 6
	v_lshl_add_u32 v25, v0, 2, s22
	s_lshl_b32 s22, s27, 2
	v_lshl_add_u32 v26, v0, 2, s22
	global_load_dwordx4 v[100:103], v23, s[0:1]
	global_load_dwordx4 v[104:107], v23, s[0:1] offset:1024
	global_load_dwordx4 v[132:135], v23, s[4:5]
	global_load_dwordx4 v[136:139], v23, s[4:5] offset:1024
	global_load_dwordx4 v[108:111], v23, s[0:1] offset:2048
	global_load_dwordx4 v[112:115], v23, s[0:1] offset:3072
	global_load_dwordx4 v[140:143], v23, s[4:5] offset:2048
	global_load_dwordx4 v[144:147], v23, s[4:5] offset:3072
	global_load_dwordx4 v[116:119], v24, s[0:1]
	global_load_dwordx4 v[120:123], v24, s[0:1] offset:1024
	global_load_dwordx4 v[148:151], v24, s[4:5]
	global_load_dwordx4 v[152:155], v24, s[4:5] offset:1024
	global_load_dwordx4 v[124:127], v24, s[0:1] offset:2048
	global_load_dwordx4 v[128:131], v24, s[0:1] offset:3072
	global_load_dwordx4 v[156:159], v24, s[4:5] offset:2048
	global_load_dwordx4 v[160:163], v24, s[4:5] offset:3072
	global_load_dword v164, v25, s[6:7]
	s_waitcnt vmcnt(26)
	v_add_f32_dpp v96, v96, v96 quad_perm:[1,0,3,2] row_mask:0xf bank_mask:0xf
	s_nop 1
	v_add_f32_dpp v96, v96, v96 quad_perm:[2,3,0,1] row_mask:0xf bank_mask:0xf
	s_nop 1
	v_add_f32_dpp v96, v96, v96 row_half_mirror row_mask:0xf bank_mask:0xf
	s_nop 1
	v_add_f32_dpp v96, v96, v96 row_mirror row_mask:0xf bank_mask:0xf
	s_nop 1
	v_mul_f32_e32 v96, 0x3a800000, v96
	v_add_f32_e32 v96, 0x358637bd, v96
	v_rsq_f32_e32 v96, v96
	s_nop 0
	v_readlane_b32 s3, v96, 0
	v_readlane_b32 s24, v96, 16
	v_readlane_b32 s98, v96, 32
	v_readlane_b32 s101, v96, 48
	s_nop 1
	v_mov_b32_e32 v184, 0
	v_mov_b32_e32 v185, 0
	v_mov_b32_e32 v186, 0
	v_mov_b32_e32 v187, 0
	v_lshlrev_b32_e32 v168, 16, v32
	v_and_b32_e32 v169, 0xffff0000, v32
	v_lshlrev_b32_e32 v170, 16, v64
	v_and_b32_e32 v171, 0xffff0000, v64
	v_mul_f32_e32 v170, s3, v170
	v_mul_f32_e32 v171, s3, v171
	v_fma_f32 v168, v170, v2, v168
	v_fma_f32 v169, v171, v3, v169
	v_fma_f32 v184, v168, v168, v184
	v_fma_f32 v184, v169, v169, v184
	v_cvt_pk_bf16_f32 v32, v168, v169
	v_lshlrev_b32_e32 v168, 16, v33
	v_and_b32_e32 v169, 0xffff0000, v33
	v_lshlrev_b32_e32 v170, 16, v65
	v_and_b32_e32 v171, 0xffff0000, v65
	v_mul_f32_e32 v170, s3, v170
	v_mul_f32_e32 v171, s3, v171
	v_fma_f32 v168, v170, v4, v168
	v_fma_f32 v169, v171, v5, v169
	v_fma_f32 v184, v168, v168, v184
	v_fma_f32 v184, v169, v169, v184
	v_cvt_pk_bf16_f32 v33, v168, v169
	v_lshlrev_b32_e32 v168, 16, v34
	v_and_b32_e32 v169, 0xffff0000, v34
	v_lshlrev_b32_e32 v170, 16, v66
	v_and_b32_e32 v171, 0xffff0000, v66
	v_mul_f32_e32 v170, s3, v170
	v_mul_f32_e32 v171, s3, v171
	v_fma_f32 v168, v170, v6, v168
	v_fma_f32 v169, v171, v7, v169
	v_fma_f32 v184, v168, v168, v184
	v_fma_f32 v184, v169, v169, v184
	v_cvt_pk_bf16_f32 v34, v168, v169
	v_lshlrev_b32_e32 v168, 16, v35
	v_and_b32_e32 v169, 0xffff0000, v35
	v_lshlrev_b32_e32 v170, 16, v67
	v_and_b32_e32 v171, 0xffff0000, v67
	v_mul_f32_e32 v170, s3, v170
	v_mul_f32_e32 v171, s3, v171
	v_fma_f32 v168, v170, v8, v168
	v_fma_f32 v169, v171, v9, v169
	v_fma_f32 v184, v168, v168, v184
	v_fma_f32 v184, v169, v169, v184
	v_cvt_pk_bf16_f32 v35, v168, v169
	v_lshlrev_b32_e32 v168, 16, v36
	v_and_b32_e32 v169, 0xffff0000, v36
	v_lshlrev_b32_e32 v170, 16, v68
	v_and_b32_e32 v171, 0xffff0000, v68
	v_mul_f32_e32 v170, s3, v170
	v_mul_f32_e32 v171, s3, v171
	v_fma_f32 v168, v170, v10, v168
	v_fma_f32 v169, v171, v11, v169
	v_fma_f32 v184, v168, v168, v184
	v_fma_f32 v184, v169, v169, v184
	v_cvt_pk_bf16_f32 v36, v168, v169
	v_lshlrev_b32_e32 v168, 16, v37
	v_and_b32_e32 v169, 0xffff0000, v37
	v_lshlrev_b32_e32 v170, 16, v69
	v_and_b32_e32 v171, 0xffff0000, v69
	v_mul_f32_e32 v170, s3, v170
	v_mul_f32_e32 v171, s3, v171
	v_fma_f32 v168, v170, v12, v168
	v_fma_f32 v169, v171, v13, v169
	v_fma_f32 v184, v168, v168, v184
	v_fma_f32 v184, v169, v169, v184
	v_cvt_pk_bf16_f32 v37, v168, v169
	v_lshlrev_b32_e32 v168, 16, v38
	v_and_b32_e32 v169, 0xffff0000, v38
	v_lshlrev_b32_e32 v170, 16, v70
	v_and_b32_e32 v171, 0xffff0000, v70
	v_mul_f32_e32 v170, s3, v170
	v_mul_f32_e32 v171, s3, v171
	v_fma_f32 v168, v170, v14, v168
	v_fma_f32 v169, v171, v15, v169
	v_fma_f32 v184, v168, v168, v184
	v_fma_f32 v184, v169, v169, v184
	v_cvt_pk_bf16_f32 v38, v168, v169
	v_lshlrev_b32_e32 v168, 16, v39
	v_and_b32_e32 v169, 0xffff0000, v39
	v_lshlrev_b32_e32 v170, 16, v71
; __device__ __forceinline__ float bf_lo(unsigned w) { return __uint_as_float(w << 16); }
; __device__ __forceinline__ float bf_hi(unsigned w) { return __uint_as_float(w & 0xffff0000u); }
; __device__ __forceinline__ unsigned pk2(float lo, float hi) { bf16x2_t r = __builtin_convertvector((f32x2_t){lo, hi}, bf16x2_t); return __builtin_bit_cast(unsigned, r); }
; template <bool SRC_F32, bool FINAL, int R> __device__ __forceinline__ void ew_compute(const EwSet<SRC_F32, R>& S, int rb, const f32x4 (&g)[4], bf16* hb_out, float* out32, float scale, float* rs_out, int lane) {
; #pragma unroll
;     for (int i = 0; i < R; ++i) {
;         float q = S.p[i];
;         q += __shfl_xor(q, 1); q += __shfl_xor(q, 2); q += __shfl_xor(q, 4); q += __shfl_xor(q, 8);
;         const float ss = __shfl(q, 0);
;         const float rs = scale / sqrtf(ss * (1.f / D) + EPS);
;         float s2 = 0.f;
; #pragma unroll
;         for (int j = 0; j < 4; ++j) {
;             f32x4 h;
;             if constexpr (SRC_F32) h = S.h32[i][j];
;             else { const v2u hw = S.hb[i][j]; h.x = bf_lo(hw.x); h.y = bf_hi(hw.x); h.z = bf_lo(hw.y); h.w = bf_hi(hw.y); }
;             const v2u fw = S.fw[i][j];
;             f32x4 v; v.x = h.x + bf_lo(fw.x) * rs * g[j].x; v.y = h.y + bf_hi(fw.x) * rs * g[j].y; v.z = h.z + bf_lo(fw.y) * rs * g[j].z; v.w = h.w + bf_hi(fw.y) * rs * g[j].w;
;             if (FINAL) __builtin_nontemporal_store(v, (f32x4*)(out32 + (size_t)(rb + i) * D) + lane + 64 * j);
;             else { v2u o; o.x = pk2(v.x, v.y); o.y = pk2(v.z, v.w); ((v2u*)(hb_out + (size_t)(rb + i) * D) + lane)[64 * j] = o; s2 += (v.x * v.x + v.y * v.y) + (v.z * v.z + v.w * v.w); }
;         }
;         if (!FINAL) { const float tot = wave_sum(s2); if (lane == 0) rs_out[rb + i] = 1.0f / sqrtf(tot * (1.f / D) + EPS); }
;     }
; }
	v_and_b32_e32 v171, 0xffff0000, v71
	v_mul_f32_e32 v170, s3, v170
	v_mul_f32_e32 v171, s3, v171
	v_fma_f32 v168, v170, v16, v168
	v_fma_f32 v169, v171, v17, v169
	v_fma_f32 v184, v168, v168, v184
	v_fma_f32 v184, v169, v169, v184
	v_cvt_pk_bf16_f32 v39, v168, v169
	global_store_dwordx4 v18, v[32:35], s[0:1]
	global_store_dwordx4 v18, v[36:39], s[0:1] offset:1024
	v_lshlrev_b32_e32 v168, 16, v40
	v_and_b32_e32 v169, 0xffff0000, v40
	v_lshlrev_b32_e32 v170, 16, v72
	v_and_b32_e32 v171, 0xffff0000, v72
	v_mul_f32_e32 v170, s24, v170
	v_mul_f32_e32 v171, s24, v171
	v_fma_f32 v168, v170, v2, v168
	v_fma_f32 v169, v171, v3, v169
	v_fma_f32 v185, v168, v168, v185
	v_fma_f32 v185, v169, v169, v185
	v_cvt_pk_bf16_f32 v40, v168, v169
	v_lshlrev_b32_e32 v168, 16, v41
	v_and_b32_e32 v169, 0xffff0000, v41
	v_lshlrev_b32_e32 v170, 16, v73
	v_and_b32_e32 v171, 0xffff0000, v73
	v_mul_f32_e32 v170, s24, v170
	v_mul_f32_e32 v171, s24, v171
	v_fma_f32 v168, v170, v4, v168
	v_fma_f32 v169, v171, v5, v169
	v_fma_f32 v185, v168, v168, v185
	v_fma_f32 v185, v169, v169, v185
	v_cvt_pk_bf16_f32 v41, v168, v169
	v_lshlrev_b32_e32 v168, 16, v42
	v_and_b32_e32 v169, 0xffff0000, v42
	v_lshlrev_b32_e32 v170, 16, v74
	v_and_b32_e32 v171, 0xffff0000, v74
	v_mul_f32_e32 v170, s24, v170
	v_mul_f32_e32 v171, s24, v171
	v_fma_f32 v168, v170, v6, v168
	v_fma_f32 v169, v171, v7, v169
	v_fma_f32 v185, v168, v168, v185
	v_fma_f32 v185, v169, v169, v185
	v_cvt_pk_bf16_f32 v42, v168, v169
	v_lshlrev_b32_e32 v168, 16, v43
	v_and_b32_e32 v169, 0xffff0000, v43
	v_lshlrev_b32_e32 v170, 16, v75
	v_and_b32_e32 v171, 0xffff0000, v75
	v_mul_f32_e32 v170, s24, v170
	v_mul_f32_e32 v171, s24, v171
	v_fma_f32 v168, v170, v8, v168
	v_fma_f32 v169, v171, v9, v169
	v_fma_f32 v185, v168, v168, v185
	v_fma_f32 v185, v169, v169, v185
	v_cvt_pk_bf16_f32 v43, v168, v169
	v_lshlrev_b32_e32 v168, 16, v44
	v_and_b32_e32 v169, 0xffff0000, v44
	v_lshlrev_b32_e32 v170, 16, v76
	v_and_b32_e32 v171, 0xffff0000, v76
	v_mul_f32_e32 v170, s24, v170
	v_mul_f32_e32 v171, s24, v171
	v_fma_f32 v168, v170, v10, v168
	v_fma_f32 v169, v171, v11, v169
	v_fma_f32 v185, v168, v168, v185
	v_fma_f32 v185, v169, v169, v185
	v_cvt_pk_bf16_f32 v44, v168, v169
	v_lshlrev_b32_e32 v168, 16, v45
	v_and_b32_e32 v169, 0xffff0000, v45
	v_lshlrev_b32_e32 v170, 16, v77
	v_and_b32_e32 v171, 0xffff0000, v77
	v_mul_f32_e32 v170, s24, v170
	v_mul_f32_e32 v171, s24, v171
	v_fma_f32 v168, v170, v12, v168
	v_fma_f32 v169, v171, v13, v169
	v_fma_f32 v185, v168, v168, v185
	v_fma_f32 v185, v169, v169, v185
	v_cvt_pk_bf16_f32 v45, v168, v169
	v_lshlrev_b32_e32 v168, 16, v46
	v_and_b32_e32 v169, 0xffff0000, v46
	v_lshlrev_b32_e32 v170, 16, v78
	v_and_b32_e32 v171, 0xffff0000, v78
	v_mul_f32_e32 v170, s24, v170
	v_mul_f32_e32 v171, s24, v171
	v_fma_f32 v168, v170, v14, v168
	v_fma_f32 v169, v171, v15, v169
	v_fma_f32 v185, v168, v168, v185
	v_fma_f32 v185, v169, v169, v185
	v_cvt_pk_bf16_f32 v46, v168, v169
	v_lshlrev_b32_e32 v168, 16, v47
	v_and_b32_e32 v169, 0xffff0000, v47
	v_lshlrev_b32_e32 v170, 16, v79
	v_and_b32_e32 v171, 0xffff0000, v79
	v_mul_f32_e32 v170, s24, v170
	v_mul_f32_e32 v171, s24, v171
	v_fma_f32 v168, v170, v16, v168
	v_fma_f32 v169, v171, v17, v169
	v_fma_f32 v185, v168, v168, v185
	v_fma_f32 v185, v169, v169, v185
	v_cvt_pk_bf16_f32 v47, v168, v169
	global_store_dwordx4 v18, v[40:43], s[0:1] offset:2048
	global_store_dwordx4 v18, v[44:47], s[0:1] offset:3072
	v_lshlrev_b32_e32 v168, 16, v48
	v_and_b32_e32 v169, 0xffff0000, v48
	v_lshlrev_b32_e32 v170, 16, v80
	v_and_b32_e32 v171, 0xffff0000, v80
	v_mul_f32_e32 v170, s98, v170
	v_mul_f32_e32 v171, s98, v171
	v_fma_f32 v168, v170, v2, v168
	v_fma_f32 v169, v171, v3, v169
	v_fma_f32 v186, v168, v168, v186
	v_fma_f32 v186, v169, v169, v186
	v_cvt_pk_bf16_f32 v48, v168, v169
	v_lshlrev_b32_e32 v168, 16, v49
	v_and_b32_e32 v169, 0xffff0000, v49
	v_lshlrev_b32_e32 v170, 16, v81
	v_and_b32_e32 v171, 0xffff0000, v81
	v_mul_f32_e32 v170, s98, v170
	v_mul_f32_e32 v171, s98, v171
	v_fma_f32 v168, v170, v4, v168
	v_fma_f32 v169, v171, v5, v169
	v_fma_f32 v186, v168, v168, v186
	v_fma_f32 v186, v169, v169, v186
	v_cvt_pk_bf16_f32 v49, v168, v169
	v_lshlrev_b32_e32 v168, 16, v50
	v_and_b32_e32 v169, 0xffff0000, v50
	v_lshlrev_b32_e32 v170, 16, v82
	v_and_b32_e32 v171, 0xffff0000, v82
	v_mul_f32_e32 v170, s98, v170
	v_mul_f32_e32 v171, s98, v171
	v_fma_f32 v168, v170, v6, v168
	v_fma_f32 v169, v171, v7, v169
	v_fma_f32 v186, v168, v168, v186
	v_fma_f32 v186, v169, v169, v186
	v_cvt_pk_bf16_f32 v50, v168, v169
	v_lshlrev_b32_e32 v168, 16, v51
	v_and_b32_e32 v169, 0xffff0000, v51
	v_lshlrev_b32_e32 v170, 16, v83
	v_and_b32_e32 v171, 0xffff0000, v83
	v_mul_f32_e32 v170, s98, v170
	v_mul_f32_e32 v171, s98, v171
	v_fma_f32 v168, v170, v8, v168
	v_fma_f32 v169, v171, v9, v169
	v_fma_f32 v186, v168, v168, v186
	v_fma_f32 v186, v169, v169, v186
	v_cvt_pk_bf16_f32 v51, v168, v169
	v_lshlrev_b32_e32 v168, 16, v52
	v_and_b32_e32 v169, 0xffff0000, v52
	v_lshlrev_b32_e32 v170, 16, v84
	v_and_b32_e32 v171, 0xffff0000, v84
	v_mul_f32_e32 v170, s98, v170
	v_mul_f32_e32 v171, s98, v171
	v_fma_f32 v168, v170, v10, v168
	v_fma_f32 v169, v171, v11, v169
	v_fma_f32 v186, v168, v168, v186
	v_fma_f32 v186, v169, v169, v186
	v_cvt_pk_bf16_f32 v52, v168, v169
	v_lshlrev_b32_e32 v168, 16, v53
	v_and_b32_e32 v169, 0xffff0000, v53
	v_lshlrev_b32_e32 v170, 16, v85
	v_and_b32_e32 v171, 0xffff0000, v85
	v_mul_f32_e32 v170, s98, v170
	v_mul_f32_e32 v171, s98, v171
	v_fma_f32 v168, v170, v12, v168
	v_fma_f32 v169, v171, v13, v169
	v_fma_f32 v186, v168, v168, v186
	v_fma_f32 v186, v169, v169, v186
	v_cvt_pk_bf16_f32 v53, v168, v169
; __device__ __forceinline__ float bf_lo(unsigned w) { return __uint_as_float(w << 16); }
; __device__ __forceinline__ float bf_hi(unsigned w) { return __uint_as_float(w & 0xffff0000u); }
; __device__ __forceinline__ unsigned pk2(float lo, float hi) { bf16x2_t r = __builtin_convertvector((f32x2_t){lo, hi}, bf16x2_t); return __builtin_bit_cast(unsigned, r); }
; template <bool SRC_F32, bool FINAL, int R> __device__ __forceinline__ void ew_compute(const EwSet<SRC_F32, R>& S, int rb, const f32x4 (&g)[4], bf16* hb_out, float* out32, float scale, float* rs_out, int lane) {
; #pragma unroll
;     for (int i = 0; i < R; ++i) {
;         float q = S.p[i];
;         q += __shfl_xor(q, 1); q += __shfl_xor(q, 2); q += __shfl_xor(q, 4); q += __shfl_xor(q, 8);
;         const float ss = __shfl(q, 0);
;         const float rs = scale / sqrtf(ss * (1.f / D) + EPS);
;         float s2 = 0.f;
; #pragma unroll
;         for (int j = 0; j < 4; ++j) {
;             f32x4 h;
;             if constexpr (SRC_F32) h = S.h32[i][j];
;             else { const v2u hw = S.hb[i][j]; h.x = bf_lo(hw.x); h.y = bf_hi(hw.x); h.z = bf_lo(hw.y); h.w = bf_hi(hw.y); }
;             const v2u fw = S.fw[i][j];
;             f32x4 v; v.x = h.x + bf_lo(fw.x) * rs * g[j].x; v.y = h.y + bf_hi(fw.x) * rs * g[j].y; v.z = h.z + bf_lo(fw.y) * rs * g[j].z; v.w = h.w + bf_hi(fw.y) * rs * g[j].w;
;             if (FINAL) __builtin_nontemporal_store(v, (f32x4*)(out32 + (size_t)(rb + i) * D) + lane + 64 * j);
;             else { v2u o; o.x = pk2(v.x, v.y); o.y = pk2(v.z, v.w); ((v2u*)(hb_out + (size_t)(rb + i) * D) + lane)[64 * j] = o; s2 += (v.x * v.x + v.y * v.y) + (v.z * v.z + v.w * v.w); }
;         }
;         if (!FINAL) { const float tot = wave_sum(s2); if (lane == 0) rs_out[rb + i] = 1.0f / sqrtf(tot * (1.f / D) + EPS); }
;     }
; }
	v_lshlrev_b32_e32 v168, 16, v54
	v_and_b32_e32 v169, 0xffff0000, v54
	v_lshlrev_b32_e32 v170, 16, v86
	v_and_b32_e32 v171, 0xffff0000, v86
	v_mul_f32_e32 v170, s98, v170
	v_mul_f32_e32 v171, s98, v171
	v_fma_f32 v168, v170, v14, v168
	v_fma_f32 v169, v171, v15, v169
	v_fma_f32 v186, v168, v168, v186
	v_fma_f32 v186, v169, v169, v186
	v_cvt_pk_bf16_f32 v54, v168, v169
	v_lshlrev_b32_e32 v168, 16, v55
	v_and_b32_e32 v169, 0xffff0000, v55
	v_lshlrev_b32_e32 v170, 16, v87
	v_and_b32_e32 v171, 0xffff0000, v87
	v_mul_f32_e32 v170, s98, v170
	v_mul_f32_e32 v171, s98, v171
	v_fma_f32 v168, v170, v16, v168
	v_fma_f32 v169, v171, v17, v169
	v_fma_f32 v186, v168, v168, v186
	v_fma_f32 v186, v169, v169, v186
	v_cvt_pk_bf16_f32 v55, v168, v169
	global_store_dwordx4 v19, v[48:51], s[0:1]
	global_store_dwordx4 v19, v[52:55], s[0:1] offset:1024
	v_lshlrev_b32_e32 v168, 16, v56
	v_and_b32_e32 v169, 0xffff0000, v56
	v_lshlrev_b32_e32 v170, 16, v88
	v_and_b32_e32 v171, 0xffff0000, v88
	v_mul_f32_e32 v170, s101, v170
	v_mul_f32_e32 v171, s101, v171
	v_fma_f32 v168, v170, v2, v168
	v_fma_f32 v169, v171, v3, v169
	v_fma_f32 v187, v168, v168, v187
	v_fma_f32 v187, v169, v169, v187
	v_cvt_pk_bf16_f32 v56, v168, v169
	v_lshlrev_b32_e32 v168, 16, v57
	v_and_b32_e32 v169, 0xffff0000, v57
	v_lshlrev_b32_e32 v170, 16, v89
	v_and_b32_e32 v171, 0xffff0000, v89
	v_mul_f32_e32 v170, s101, v170
	v_mul_f32_e32 v171, s101, v171
	v_fma_f32 v168, v170, v4, v168
	v_fma_f32 v169, v171, v5, v169
	v_fma_f32 v187, v168, v168, v187
	v_fma_f32 v187, v169, v169, v187
	v_cvt_pk_bf16_f32 v57, v168, v169
	v_lshlrev_b32_e32 v168, 16, v58
	v_and_b32_e32 v169, 0xffff0000, v58
	v_lshlrev_b32_e32 v170, 16, v90
	v_and_b32_e32 v171, 0xffff0000, v90
	v_mul_f32_e32 v170, s101, v170
	v_mul_f32_e32 v171, s101, v171
	v_fma_f32 v168, v170, v6, v168
	v_fma_f32 v169, v171, v7, v169
	v_fma_f32 v187, v168, v168, v187
	v_fma_f32 v187, v169, v169, v187
	v_cvt_pk_bf16_f32 v58, v168, v169
	v_lshlrev_b32_e32 v168, 16, v59
	v_and_b32_e32 v169, 0xffff0000, v59
	v_lshlrev_b32_e32 v170, 16, v91
	v_and_b32_e32 v171, 0xffff0000, v91
	v_mul_f32_e32 v170, s101, v170
	v_mul_f32_e32 v171, s101, v171
	v_fma_f32 v168, v170, v8, v168
	v_fma_f32 v169, v171, v9, v169
	v_fma_f32 v187, v168, v168, v187
	v_fma_f32 v187, v169, v169, v187
	v_cvt_pk_bf16_f32 v59, v168, v169
	v_lshlrev_b32_e32 v168, 16, v60
	v_and_b32_e32 v169, 0xffff0000, v60
	v_lshlrev_b32_e32 v170, 16, v92
	v_and_b32_e32 v171, 0xffff0000, v92
	v_mul_f32_e32 v170, s101, v170
	v_mul_f32_e32 v171, s101, v171
	v_fma_f32 v168, v170, v10, v168
	v_fma_f32 v169, v171, v11, v169
	v_fma_f32 v187, v168, v168, v187
	v_fma_f32 v187, v169, v169, v187
	v_cvt_pk_bf16_f32 v60, v168, v169
	v_lshlrev_b32_e32 v168, 16, v61
	v_and_b32_e32 v169, 0xffff0000, v61
	v_lshlrev_b32_e32 v170, 16, v93
	v_and_b32_e32 v171, 0xffff0000, v93
	v_mul_f32_e32 v170, s101, v170
	v_mul_f32_e32 v171, s101, v171
	v_fma_f32 v168, v170, v12, v168
	v_fma_f32 v169, v171, v13, v169
	v_fma_f32 v187, v168, v168, v187
	v_fma_f32 v187, v169, v169, v187
	v_cvt_pk_bf16_f32 v61, v168, v169
	v_lshlrev_b32_e32 v168, 16, v62
	v_and_b32_e32 v169, 0xffff0000, v62
	v_lshlrev_b32_e32 v170, 16, v94
	v_and_b32_e32 v171, 0xffff0000, v94
	v_mul_f32_e32 v170, s101, v170
	v_mul_f32_e32 v171, s101, v171
	v_fma_f32 v168, v170, v14, v168
	v_fma_f32 v169, v171, v15, v169
	v_fma_f32 v187, v168, v168, v187
	v_fma_f32 v187, v169, v169, v187
	v_cvt_pk_bf16_f32 v62, v168, v169
	v_lshlrev_b32_e32 v168, 16, v63
	v_and_b32_e32 v169, 0xffff0000, v63
	v_lshlrev_b32_e32 v170, 16, v95
	v_and_b32_e32 v171, 0xffff0000, v95
	v_mul_f32_e32 v170, s101, v170
	v_mul_f32_e32 v171, s101, v171
	v_fma_f32 v168, v170, v16, v168
	v_fma_f32 v169, v171, v17, v169
	v_fma_f32 v187, v168, v168, v187
	v_fma_f32 v187, v169, v169, v187
	v_cvt_pk_bf16_f32 v63, v168, v169
	global_store_dwordx4 v19, v[56:59], s[0:1] offset:2048
	global_store_dwordx4 v19, v[60:63], s[0:1] offset:3072
	s_nop 1
	v_add_f32_dpp v184, v184, v184 quad_perm:[1,0,3,2] row_mask:0xf bank_mask:0xf
	v_add_f32_dpp v185, v185, v185 quad_perm:[1,0,3,2] row_mask:0xf bank_mask:0xf
	v_add_f32_dpp v186, v186, v186 quad_perm:[1,0,3,2] row_mask:0xf bank_mask:0xf
	v_add_f32_dpp v187, v187, v187 quad_perm:[1,0,3,2] row_mask:0xf bank_mask:0xf
	v_add_f32_dpp v184, v184, v184 quad_perm:[2,3,0,1] row_mask:0xf bank_mask:0xf
	v_add_f32_dpp v185, v185, v185 quad_perm:[2,3,0,1] row_mask:0xf bank_mask:0xf
	v_add_f32_dpp v186, v186, v186 quad_perm:[2,3,0,1] row_mask:0xf bank_mask:0xf
	v_add_f32_dpp v187, v187, v187 quad_perm:[2,3,0,1] row_mask:0xf bank_mask:0xf
	v_add_f32_dpp v184, v184, v184 row_half_mirror row_mask:0xf bank_mask:0xf
	v_add_f32_dpp v185, v185, v185 row_half_mirror row_mask:0xf bank_mask:0xf
	v_add_f32_dpp v186, v186, v186 row_half_mirror row_mask:0xf bank_mask:0xf
	v_add_f32_dpp v187, v187, v187 row_half_mirror row_mask:0xf bank_mask:0xf
	v_add_f32_dpp v184, v184, v184 row_mirror row_mask:0xf bank_mask:0xf
	v_add_f32_dpp v185, v185, v185 row_mirror row_mask:0xf bank_mask:0xf
	v_add_f32_dpp v186, v186, v186 row_mirror row_mask:0xf bank_mask:0xf
	v_add_f32_dpp v187, v187, v187 row_mirror row_mask:0xf bank_mask:0xf
	v_add_f32_dpp v184, v184, v184 row_bcast:15 row_mask:0xa bank_mask:0xf
	v_add_f32_dpp v185, v185, v185 row_bcast:15 row_mask:0xa bank_mask:0xf
	v_add_f32_dpp v186, v186, v186 row_bcast:15 row_mask:0xa bank_mask:0xf
	v_add_f32_dpp v187, v187, v187 row_bcast:15 row_mask:0xa bank_mask:0xf
	v_add_f32_dpp v184, v184, v184 row_bcast:31 row_mask:0xc bank_mask:0xf
	v_add_f32_dpp v185, v185, v185 row_bcast:31 row_mask:0xc bank_mask:0xf
	v_add_f32_dpp v186, v186, v186 row_bcast:31 row_mask:0xc bank_mask:0xf
	v_add_f32_dpp v187, v187, v187 row_bcast:31 row_mask:0xc bank_mask:0xf
	s_nop 1
	v_readlane_b32 s3, v184, 63
	v_readlane_b32 s24, v185, 63
	v_readlane_b32 s98, v186, 63
	v_readlane_b32 s101, v187, 63
	s_nop 3
	v_writelane_b32 v188, s3, 0
	v_writelane_b32 v188, s24, 1
	v_writelane_b32 v188, s98, 2
	v_writelane_b32 v188, s101, 3
	s_nop 1
	v_mul_f32_e32 v188, 0x3a800000, v188
	v_add_f32_e32 v188, 0x358637bd, v188
	v_rsq_f32_e32 v188, v188
	s_mov_b64 exec, 15
	global_store_dword v21, v188, s[14:15]
	s_mov_b64 exec, -1
	s_waitcnt vmcnt(9)
; __device__ __forceinline__ float bf_lo(unsigned w) { return __uint_as_float(w << 16); }
; __device__ __forceinline__ float bf_hi(unsigned w) { return __uint_as_float(w & 0xffff0000u); }
; __device__ __forceinline__ unsigned pk2(float lo, float hi) { bf16x2_t r = __builtin_convertvector((f32x2_t){lo, hi}, bf16x2_t); return __builtin_bit_cast(unsigned, r); }
; template <bool SRC_F32, bool FINAL, int R> __device__ __forceinline__ void ew_compute(const EwSet<SRC_F32, R>& S, int rb, const f32x4 (&g)[4], bf16* hb_out, float* out32, float scale, float* rs_out, int lane) {
; #pragma unroll
;     for (int i = 0; i < R; ++i) {
;         float q = S.p[i];
;         q += __shfl_xor(q, 1); q += __shfl_xor(q, 2); q += __shfl_xor(q, 4); q += __shfl_xor(q, 8);
;         const float ss = __shfl(q, 0);
;         const float rs = scale / sqrtf(ss * (1.f / D) + EPS);
;         float s2 = 0.f;
; #pragma unroll
;         for (int j = 0; j < 4; ++j) {
;             f32x4 h;
;             if constexpr (SRC_F32) h = S.h32[i][j];
;             else { const v2u hw = S.hb[i][j]; h.x = bf_lo(hw.x); h.y = bf_hi(hw.x); h.z = bf_lo(hw.y); h.w = bf_hi(hw.y); }
;             const v2u fw = S.fw[i][j];
;             f32x4 v; v.x = h.x + bf_lo(fw.x) * rs * g[j].x; v.y = h.y + bf_hi(fw.x) * rs * g[j].y; v.z = h.z + bf_lo(fw.y) * rs * g[j].z; v.w = h.w + bf_hi(fw.y) * rs * g[j].w;
;             if (FINAL) __builtin_nontemporal_store(v, (f32x4*)(out32 + (size_t)(rb + i) * D) + lane + 64 * j);
;             else { v2u o; o.x = pk2(v.x, v.y); o.y = pk2(v.z, v.w); ((v2u*)(hb_out + (size_t)(rb + i) * D) + lane)[64 * j] = o; s2 += (v.x * v.x + v.y * v.y) + (v.z * v.z + v.w * v.w); }
;         }
;         if (!FINAL) { const float tot = wave_sum(s2); if (lane == 0) rs_out[rb + i] = 1.0f / sqrtf(tot * (1.f / D) + EPS); }
;     }
; }
	v_add_f32_dpp v164, v164, v164 quad_perm:[1,0,3,2] row_mask:0xf bank_mask:0xf
	s_nop 1
	v_add_f32_dpp v164, v164, v164 quad_perm:[2,3,0,1] row_mask:0xf bank_mask:0xf
	s_nop 1
	v_add_f32_dpp v164, v164, v164 row_half_mirror row_mask:0xf bank_mask:0xf
	s_nop 1
	v_add_f32_dpp v164, v164, v164 row_mirror row_mask:0xf bank_mask:0xf
	s_nop 1
	v_mul_f32_e32 v164, 0x3a800000, v164
	v_add_f32_e32 v164, 0x358637bd, v164
	v_rsq_f32_e32 v164, v164
	s_nop 0
	v_readlane_b32 s3, v164, 0
	v_readlane_b32 s24, v164, 16
	v_readlane_b32 s98, v164, 32
	v_readlane_b32 s101, v164, 48
	s_nop 1
	v_mov_b32_e32 v184, 0
	v_mov_b32_e32 v185, 0
	v_mov_b32_e32 v186, 0
	v_mov_b32_e32 v187, 0
	v_lshlrev_b32_e32 v168, 16, v100
	v_and_b32_e32 v169, 0xffff0000, v100
	v_lshlrev_b32_e32 v170, 16, v132
	v_and_b32_e32 v171, 0xffff0000, v132
	v_mul_f32_e32 v170, s3, v170
	v_mul_f32_e32 v171, s3, v171
	v_fma_f32 v168, v170, v2, v168
	v_fma_f32 v169, v171, v3, v169
	v_fma_f32 v184, v168, v168, v184
	v_fma_f32 v184, v169, v169, v184
	v_cvt_pk_bf16_f32 v100, v168, v169
	v_lshlrev_b32_e32 v168, 16, v101
	v_and_b32_e32 v169, 0xffff0000, v101
	v_lshlrev_b32_e32 v170, 16, v133
	v_and_b32_e32 v171, 0xffff0000, v133
	v_mul_f32_e32 v170, s3, v170
	v_mul_f32_e32 v171, s3, v171
	v_fma_f32 v168, v170, v4, v168
	v_fma_f32 v169, v171, v5, v169
	v_fma_f32 v184, v168, v168, v184
	v_fma_f32 v184, v169, v169, v184
	v_cvt_pk_bf16_f32 v101, v168, v169
	v_lshlrev_b32_e32 v168, 16, v102
	v_and_b32_e32 v169, 0xffff0000, v102
	v_lshlrev_b32_e32 v170, 16, v134
	v_and_b32_e32 v171, 0xffff0000, v134
	v_mul_f32_e32 v170, s3, v170
	v_mul_f32_e32 v171, s3, v171
	v_fma_f32 v168, v170, v6, v168
	v_fma_f32 v169, v171, v7, v169
	v_fma_f32 v184, v168, v168, v184
	v_fma_f32 v184, v169, v169, v184
	v_cvt_pk_bf16_f32 v102, v168, v169
	v_lshlrev_b32_e32 v168, 16, v103
	v_and_b32_e32 v169, 0xffff0000, v103
	v_lshlrev_b32_e32 v170, 16, v135
	v_and_b32_e32 v171, 0xffff0000, v135
	v_mul_f32_e32 v170, s3, v170
	v_mul_f32_e32 v171, s3, v171
	v_fma_f32 v168, v170, v8, v168
	v_fma_f32 v169, v171, v9, v169
	v_fma_f32 v184, v168, v168, v184
	v_fma_f32 v184, v169, v169, v184
	v_cvt_pk_bf16_f32 v103, v168, v169
	v_lshlrev_b32_e32 v168, 16, v104
	v_and_b32_e32 v169, 0xffff0000, v104
	v_lshlrev_b32_e32 v170, 16, v136
	v_and_b32_e32 v171, 0xffff0000, v136
	v_mul_f32_e32 v170, s3, v170
	v_mul_f32_e32 v171, s3, v171
	v_fma_f32 v168, v170, v10, v168
	v_fma_f32 v169, v171, v11, v169
	v_fma_f32 v184, v168, v168, v184
	v_fma_f32 v184, v169, v169, v184
	v_cvt_pk_bf16_f32 v104, v168, v169
	v_lshlrev_b32_e32 v168, 16, v105
	v_and_b32_e32 v169, 0xffff0000, v105
	v_lshlrev_b32_e32 v170, 16, v137
	v_and_b32_e32 v171, 0xffff0000, v137
	v_mul_f32_e32 v170, s3, v170
	v_mul_f32_e32 v171, s3, v171
	v_fma_f32 v168, v170, v12, v168
	v_fma_f32 v169, v171, v13, v169
	v_fma_f32 v184, v168, v168, v184
	v_fma_f32 v184, v169, v169, v184
	v_cvt_pk_bf16_f32 v105, v168, v169
	v_lshlrev_b32_e32 v168, 16, v106
	v_and_b32_e32 v169, 0xffff0000, v106
	v_lshlrev_b32_e32 v170, 16, v138
	v_and_b32_e32 v171, 0xffff0000, v138
	v_mul_f32_e32 v170, s3, v170
	v_mul_f32_e32 v171, s3, v171
	v_fma_f32 v168, v170, v14, v168
	v_fma_f32 v169, v171, v15, v169
	v_fma_f32 v184, v168, v168, v184
	v_fma_f32 v184, v169, v169, v184
	v_cvt_pk_bf16_f32 v106, v168, v169
	v_lshlrev_b32_e32 v168, 16, v107
	v_and_b32_e32 v169, 0xffff0000, v107
	v_lshlrev_b32_e32 v170, 16, v139
	v_and_b32_e32 v171, 0xffff0000, v139
	v_mul_f32_e32 v170, s3, v170
	v_mul_f32_e32 v171, s3, v171
	v_fma_f32 v168, v170, v16, v168
	v_fma_f32 v169, v171, v17, v169
	v_fma_f32 v184, v168, v168, v184
	v_fma_f32 v184, v169, v169, v184
	v_cvt_pk_bf16_f32 v107, v168, v169
	global_store_dwordx4 v23, v[100:103], s[0:1]
	global_store_dwordx4 v23, v[104:107], s[0:1] offset:1024
	v_lshlrev_b32_e32 v168, 16, v108
	v_and_b32_e32 v169, 0xffff0000, v108
	v_lshlrev_b32_e32 v170, 16, v140
	v_and_b32_e32 v171, 0xffff0000, v140
	v_mul_f32_e32 v170, s24, v170
	v_mul_f32_e32 v171, s24, v171
	v_fma_f32 v168, v170, v2, v168
	v_fma_f32 v169, v171, v3, v169
	v_fma_f32 v185, v168, v168, v185
	v_fma_f32 v185, v169, v169, v185
	v_cvt_pk_bf16_f32 v108, v168, v169
	v_lshlrev_b32_e32 v168, 16, v109
	v_and_b32_e32 v169, 0xffff0000, v109
	v_lshlrev_b32_e32 v170, 16, v141
	v_and_b32_e32 v171, 0xffff0000, v141
	v_mul_f32_e32 v170, s24, v170
	v_mul_f32_e32 v171, s24, v171
	v_fma_f32 v168, v170, v4, v168
	v_fma_f32 v169, v171, v5, v169
	v_fma_f32 v185, v168, v168, v185
	v_fma_f32 v185, v169, v169, v185
	v_cvt_pk_bf16_f32 v109, v168, v169
	v_lshlrev_b32_e32 v168, 16, v110
	v_and_b32_e32 v169, 0xffff0000, v110
	v_lshlrev_b32_e32 v170, 16, v142
	v_and_b32_e32 v171, 0xffff0000, v142
	v_mul_f32_e32 v170, s24, v170
	v_mul_f32_e32 v171, s24, v171
	v_fma_f32 v168, v170, v6, v168
	v_fma_f32 v169, v171, v7, v169
	v_fma_f32 v185, v168, v168, v185
	v_fma_f32 v185, v169, v169, v185
	v_cvt_pk_bf16_f32 v110, v168, v169
	v_lshlrev_b32_e32 v168, 16, v111
	v_and_b32_e32 v169, 0xffff0000, v111
	v_lshlrev_b32_e32 v170, 16, v143
	v_and_b32_e32 v171, 0xffff0000, v143
	v_mul_f32_e32 v170, s24, v170
	v_mul_f32_e32 v171, s24, v171
	v_fma_f32 v168, v170, v8, v168
	v_fma_f32 v169, v171, v9, v169
	v_fma_f32 v185, v168, v168, v185
	v_fma_f32 v185, v169, v169, v185
	v_cvt_pk_bf16_f32 v111, v168, v169
	v_lshlrev_b32_e32 v168, 16, v112
	v_and_b32_e32 v169, 0xffff0000, v112
	v_lshlrev_b32_e32 v170, 16, v144
	v_and_b32_e32 v171, 0xffff0000, v144
	v_mul_f32_e32 v170, s24, v170
	v_mul_f32_e32 v171, s24, v171
	v_fma_f32 v168, v170, v10, v168
	v_fma_f32 v169, v171, v11, v169
	v_fma_f32 v185, v168, v168, v185
	v_fma_f32 v185, v169, v169, v185
	v_cvt_pk_bf16_f32 v112, v168, v169
; __device__ __forceinline__ float bf_lo(unsigned w) { return __uint_as_float(w << 16); }
; __device__ __forceinline__ float bf_hi(unsigned w) { return __uint_as_float(w & 0xffff0000u); }
; __device__ __forceinline__ unsigned pk2(float lo, float hi) { bf16x2_t r = __builtin_convertvector((f32x2_t){lo, hi}, bf16x2_t); return __builtin_bit_cast(unsigned, r); }
; template <bool SRC_F32, bool FINAL, int R> __device__ __forceinline__ void ew_compute(const EwSet<SRC_F32, R>& S, int rb, const f32x4 (&g)[4], bf16* hb_out, float* out32, float scale, float* rs_out, int lane) {
; #pragma unroll
;     for (int i = 0; i < R; ++i) {
;         float q = S.p[i];
;         q += __shfl_xor(q, 1); q += __shfl_xor(q, 2); q += __shfl_xor(q, 4); q += __shfl_xor(q, 8);
;         const float ss = __shfl(q, 0);
;         const float rs = scale / sqrtf(ss * (1.f / D) + EPS);
;         float s2 = 0.f;
; #pragma unroll
;         for (int j = 0; j < 4; ++j) {
;             f32x4 h;
;             if constexpr (SRC_F32) h = S.h32[i][j];
;             else { const v2u hw = S.hb[i][j]; h.x = bf_lo(hw.x); h.y = bf_hi(hw.x); h.z = bf_lo(hw.y); h.w = bf_hi(hw.y); }
;             const v2u fw = S.fw[i][j];
;             f32x4 v; v.x = h.x + bf_lo(fw.x) * rs * g[j].x; v.y = h.y + bf_hi(fw.x) * rs * g[j].y; v.z = h.z + bf_lo(fw.y) * rs * g[j].z; v.w = h.w + bf_hi(fw.y) * rs * g[j].w;
;             if (FINAL) __builtin_nontemporal_store(v, (f32x4*)(out32 + (size_t)(rb + i) * D) + lane + 64 * j);
;             else { v2u o; o.x = pk2(v.x, v.y); o.y = pk2(v.z, v.w); ((v2u*)(hb_out + (size_t)(rb + i) * D) + lane)[64 * j] = o; s2 += (v.x * v.x + v.y * v.y) + (v.z * v.z + v.w * v.w); }
;         }
;         if (!FINAL) { const float tot = wave_sum(s2); if (lane == 0) rs_out[rb + i] = 1.0f / sqrtf(tot * (1.f / D) + EPS); }
;     }
; }
	v_lshlrev_b32_e32 v168, 16, v113
	v_and_b32_e32 v169, 0xffff0000, v113
	v_lshlrev_b32_e32 v170, 16, v145
	v_and_b32_e32 v171, 0xffff0000, v145
	v_mul_f32_e32 v170, s24, v170
	v_mul_f32_e32 v171, s24, v171
	v_fma_f32 v168, v170, v12, v168
	v_fma_f32 v169, v171, v13, v169
	v_fma_f32 v185, v168, v168, v185
	v_fma_f32 v185, v169, v169, v185
	v_cvt_pk_bf16_f32 v113, v168, v169
	v_lshlrev_b32_e32 v168, 16, v114
	v_and_b32_e32 v169, 0xffff0000, v114
	v_lshlrev_b32_e32 v170, 16, v146
	v_and_b32_e32 v171, 0xffff0000, v146
	v_mul_f32_e32 v170, s24, v170
	v_mul_f32_e32 v171, s24, v171
	v_fma_f32 v168, v170, v14, v168
	v_fma_f32 v169, v171, v15, v169
	v_fma_f32 v185, v168, v168, v185
	v_fma_f32 v185, v169, v169, v185
	v_cvt_pk_bf16_f32 v114, v168, v169
	v_lshlrev_b32_e32 v168, 16, v115
	v_and_b32_e32 v169, 0xffff0000, v115
	v_lshlrev_b32_e32 v170, 16, v147
	v_and_b32_e32 v171, 0xffff0000, v147
	v_mul_f32_e32 v170, s24, v170
	v_mul_f32_e32 v171, s24, v171
	v_fma_f32 v168, v170, v16, v168
	v_fma_f32 v169, v171, v17, v169
	v_fma_f32 v185, v168, v168, v185
	v_fma_f32 v185, v169, v169, v185
	v_cvt_pk_bf16_f32 v115, v168, v169
	global_store_dwordx4 v23, v[108:111], s[0:1] offset:2048
	global_store_dwordx4 v23, v[112:115], s[0:1] offset:3072
	v_lshlrev_b32_e32 v168, 16, v116
	v_and_b32_e32 v169, 0xffff0000, v116
	v_lshlrev_b32_e32 v170, 16, v148
	v_and_b32_e32 v171, 0xffff0000, v148
	v_mul_f32_e32 v170, s98, v170
	v_mul_f32_e32 v171, s98, v171
	v_fma_f32 v168, v170, v2, v168
	v_fma_f32 v169, v171, v3, v169
	v_fma_f32 v186, v168, v168, v186
	v_fma_f32 v186, v169, v169, v186
	v_cvt_pk_bf16_f32 v116, v168, v169
	v_lshlrev_b32_e32 v168, 16, v117
	v_and_b32_e32 v169, 0xffff0000, v117
	v_lshlrev_b32_e32 v170, 16, v149
	v_and_b32_e32 v171, 0xffff0000, v149
	v_mul_f32_e32 v170, s98, v170
	v_mul_f32_e32 v171, s98, v171
	v_fma_f32 v168, v170, v4, v168
	v_fma_f32 v169, v171, v5, v169
	v_fma_f32 v186, v168, v168, v186
	v_fma_f32 v186, v169, v169, v186
	v_cvt_pk_bf16_f32 v117, v168, v169
	v_lshlrev_b32_e32 v168, 16, v118
	v_and_b32_e32 v169, 0xffff0000, v118
	v_lshlrev_b32_e32 v170, 16, v150
	v_and_b32_e32 v171, 0xffff0000, v150
	v_mul_f32_e32 v170, s98, v170
	v_mul_f32_e32 v171, s98, v171
	v_fma_f32 v168, v170, v6, v168
	v_fma_f32 v169, v171, v7, v169
	v_fma_f32 v186, v168, v168, v186
	v_fma_f32 v186, v169, v169, v186
	v_cvt_pk_bf16_f32 v118, v168, v169
	v_lshlrev_b32_e32 v168, 16, v119
	v_and_b32_e32 v169, 0xffff0000, v119
	v_lshlrev_b32_e32 v170, 16, v151
	v_and_b32_e32 v171, 0xffff0000, v151
	v_mul_f32_e32 v170, s98, v170
	v_mul_f32_e32 v171, s98, v171
	v_fma_f32 v168, v170, v8, v168
	v_fma_f32 v169, v171, v9, v169
	v_fma_f32 v186, v168, v168, v186
	v_fma_f32 v186, v169, v169, v186
	v_cvt_pk_bf16_f32 v119, v168, v169
	v_lshlrev_b32_e32 v168, 16, v120
	v_and_b32_e32 v169, 0xffff0000, v120
	v_lshlrev_b32_e32 v170, 16, v152
	v_and_b32_e32 v171, 0xffff0000, v152
	v_mul_f32_e32 v170, s98, v170
	v_mul_f32_e32 v171, s98, v171
	v_fma_f32 v168, v170, v10, v168
	v_fma_f32 v169, v171, v11, v169
	v_fma_f32 v186, v168, v168, v186
	v_fma_f32 v186, v169, v169, v186
	v_cvt_pk_bf16_f32 v120, v168, v169
	v_lshlrev_b32_e32 v168, 16, v121
	v_and_b32_e32 v169, 0xffff0000, v121
	v_lshlrev_b32_e32 v170, 16, v153
	v_and_b32_e32 v171, 0xffff0000, v153
	v_mul_f32_e32 v170, s98, v170
	v_mul_f32_e32 v171, s98, v171
	v_fma_f32 v168, v170, v12, v168
	v_fma_f32 v169, v171, v13, v169
	v_fma_f32 v186, v168, v168, v186
	v_fma_f32 v186, v169, v169, v186
	v_cvt_pk_bf16_f32 v121, v168, v169
	v_lshlrev_b32_e32 v168, 16, v122
	v_and_b32_e32 v169, 0xffff0000, v122
	v_lshlrev_b32_e32 v170, 16, v154
	v_and_b32_e32 v171, 0xffff0000, v154
	v_mul_f32_e32 v170, s98, v170
	v_mul_f32_e32 v171, s98, v171
	v_fma_f32 v168, v170, v14, v168
	v_fma_f32 v169, v171, v15, v169
	v_fma_f32 v186, v168, v168, v186
	v_fma_f32 v186, v169, v169, v186
	v_cvt_pk_bf16_f32 v122, v168, v169
	v_lshlrev_b32_e32 v168, 16, v123
	v_and_b32_e32 v169, 0xffff0000, v123
	v_lshlrev_b32_e32 v170, 16, v155
	v_and_b32_e32 v171, 0xffff0000, v155
	v_mul_f32_e32 v170, s98, v170
	v_mul_f32_e32 v171, s98, v171
	v_fma_f32 v168, v170, v16, v168
	v_fma_f32 v169, v171, v17, v169
	v_fma_f32 v186, v168, v168, v186
	v_fma_f32 v186, v169, v169, v186
	v_cvt_pk_bf16_f32 v123, v168, v169
	global_store_dwordx4 v24, v[116:119], s[0:1]
	global_store_dwordx4 v24, v[120:123], s[0:1] offset:1024
	v_lshlrev_b32_e32 v168, 16, v124
	v_and_b32_e32 v169, 0xffff0000, v124
	v_lshlrev_b32_e32 v170, 16, v156
	v_and_b32_e32 v171, 0xffff0000, v156
	v_mul_f32_e32 v170, s101, v170
	v_mul_f32_e32 v171, s101, v171
	v_fma_f32 v168, v170, v2, v168
	v_fma_f32 v169, v171, v3, v169
	v_fma_f32 v187, v168, v168, v187
	v_fma_f32 v187, v169, v169, v187
	v_cvt_pk_bf16_f32 v124, v168, v169
	v_lshlrev_b32_e32 v168, 16, v125
	v_and_b32_e32 v169, 0xffff0000, v125
	v_lshlrev_b32_e32 v170, 16, v157
	v_and_b32_e32 v171, 0xffff0000, v157
	v_mul_f32_e32 v170, s101, v170
	v_mul_f32_e32 v171, s101, v171
	v_fma_f32 v168, v170, v4, v168
	v_fma_f32 v169, v171, v5, v169
	v_fma_f32 v187, v168, v168, v187
	v_fma_f32 v187, v169, v169, v187
	v_cvt_pk_bf16_f32 v125, v168, v169
	v_lshlrev_b32_e32 v168, 16, v126
	v_and_b32_e32 v169, 0xffff0000, v126
; __device__ __forceinline__ float bf_lo(unsigned w) { return __uint_as_float(w << 16); }
; __device__ __forceinline__ float bf_hi(unsigned w) { return __uint_as_float(w & 0xffff0000u); }
; template <bool SRC_F32, bool FINAL, int R> __device__ __forceinline__ void ew_compute(const EwSet<SRC_F32, R>& S, int rb, const f32x4 (&g)[4], bf16* hb_out, float* out32, float scale, float* rs_out, int lane) {
; #pragma unroll
;     for (int i = 0; i < R; ++i) {
;         float q = S.p[i];
;         q += __shfl_xor(q, 1); q += __shfl_xor(q, 2); q += __shfl_xor(q, 4); q += __shfl_xor(q, 8);
;         const float ss = __shfl(q, 0);
;         const float rs = scale / sqrtf(ss * (1.f / D) + EPS);
;         float s2 = 0.f;
; #pragma unroll
;         for (int j = 0; j < 4; ++j) {
;             f32x4 h;
;             if constexpr (SRC_F32) h = S.h32[i][j];
;             else { const v2u hw = S.hb[i][j]; h.x = bf_lo(hw.x); h.y = bf_hi(hw.x); h.z = bf_lo(hw.y); h.w = bf_hi(hw.y); }
;             const v2u fw = S.fw[i][j];
;             f32x4 v; v.x = h.x + bf_lo(fw.x) * rs * g[j].x; v.y = h.y + bf_hi(fw.x) * rs * g[j].y; v.z = h.z + bf_lo(fw.y) * rs * g[j].z; v.w = h.w + bf_hi(fw.y) * rs * g[j].w;
;             if (FINAL) __builtin_nontemporal_store(v, (f32x4*)(out32 + (size_t)(rb + i) * D) + lane + 64 * j);
;             else { v2u o; o.x = pk2(v.x, v.y); o.y = pk2(v.z, v.w); ((v2u*)(hb_out + (size_t)(rb + i) * D) + lane)[64 * j] = o; s2 += (v.x * v.x + v.y * v.y) + (v.z * v.z + v.w * v.w); }
;         }
;         if (!FINAL) { const float tot = wave_sum(s2); if (lane == 0) rs_out[rb + i] = 1.0f / sqrtf(tot * (1.f / D) + EPS); }
;     }
; }
; __device__ __forceinline__ void xcd_barrier(const XcdBarrier& b) {
;     asm volatile("s_waitcnt vmcnt(0)" ::: "memory");
;     __syncthreads();
;     if (threadIdx.x == 0) {
;         unsigned* bar = b.bar;
;         __builtin_amdgcn_s_waitcnt(0);
;         unsigned nloc = b.st[0], nx = b.st[1];
;         if (nloc == 0u) { xcd_barrier_complete(bar, b.x, nloc, nx); b.st[0] = nloc; b.st[1] = nx; }
;         const unsigned old = xb_add(&bar[XB_XSUB(b.x)], 1u);
;         const unsigned gen = old / nloc;
;         if (old + 1u == (gen + 1u) * nloc) {
;             __builtin_amdgcn_fence(__ATOMIC_RELEASE, "agent");
;             asm volatile("s_waitcnt vmcnt(0)" ::: "memory");
;             const unsigned og = xb_add(&bar[XB_TOP], 1u);
	v_lshlrev_b32_e32 v170, 16, v158
	v_and_b32_e32 v171, 0xffff0000, v158
	v_mul_f32_e32 v170, s101, v170
	v_mul_f32_e32 v171, s101, v171
	v_fma_f32 v168, v170, v6, v168
	v_fma_f32 v169, v171, v7, v169
	v_fma_f32 v187, v168, v168, v187
	v_fma_f32 v187, v169, v169, v187
	v_cvt_pk_bf16_f32 v126, v168, v169
	v_lshlrev_b32_e32 v168, 16, v127
	v_and_b32_e32 v169, 0xffff0000, v127
	v_lshlrev_b32_e32 v170, 16, v159
	v_and_b32_e32 v171, 0xffff0000, v159
	v_mul_f32_e32 v170, s101, v170
	v_mul_f32_e32 v171, s101, v171
	v_fma_f32 v168, v170, v8, v168
	v_fma_f32 v169, v171, v9, v169
	v_fma_f32 v187, v168, v168, v187
	v_fma_f32 v187, v169, v169, v187
	v_cvt_pk_bf16_f32 v127, v168, v169
	v_lshlrev_b32_e32 v168, 16, v128
	v_and_b32_e32 v169, 0xffff0000, v128
	v_lshlrev_b32_e32 v170, 16, v160
	v_and_b32_e32 v171, 0xffff0000, v160
	v_mul_f32_e32 v170, s101, v170
	v_mul_f32_e32 v171, s101, v171
	v_fma_f32 v168, v170, v10, v168
	v_fma_f32 v169, v171, v11, v169
	v_fma_f32 v187, v168, v168, v187
	v_fma_f32 v187, v169, v169, v187
	v_cvt_pk_bf16_f32 v128, v168, v169
	v_lshlrev_b32_e32 v168, 16, v129
	v_and_b32_e32 v169, 0xffff0000, v129
	v_lshlrev_b32_e32 v170, 16, v161
	v_and_b32_e32 v171, 0xffff0000, v161
	v_mul_f32_e32 v170, s101, v170
	v_mul_f32_e32 v171, s101, v171
	v_fma_f32 v168, v170, v12, v168
	v_fma_f32 v169, v171, v13, v169
	v_fma_f32 v187, v168, v168, v187
	v_fma_f32 v187, v169, v169, v187
	v_cvt_pk_bf16_f32 v129, v168, v169
	v_lshlrev_b32_e32 v168, 16, v130
	v_and_b32_e32 v169, 0xffff0000, v130
	v_lshlrev_b32_e32 v170, 16, v162
	v_and_b32_e32 v171, 0xffff0000, v162
	v_mul_f32_e32 v170, s101, v170
	v_mul_f32_e32 v171, s101, v171
	v_fma_f32 v168, v170, v14, v168
	v_fma_f32 v169, v171, v15, v169
	v_fma_f32 v187, v168, v168, v187
	v_fma_f32 v187, v169, v169, v187
	v_cvt_pk_bf16_f32 v130, v168, v169
	v_lshlrev_b32_e32 v168, 16, v131
	v_and_b32_e32 v169, 0xffff0000, v131
	v_lshlrev_b32_e32 v170, 16, v163
	v_and_b32_e32 v171, 0xffff0000, v163
	v_mul_f32_e32 v170, s101, v170
	v_mul_f32_e32 v171, s101, v171
	v_fma_f32 v168, v170, v16, v168
	v_fma_f32 v169, v171, v17, v169
	v_fma_f32 v187, v168, v168, v187
	v_fma_f32 v187, v169, v169, v187
	v_cvt_pk_bf16_f32 v131, v168, v169
	global_store_dwordx4 v24, v[124:127], s[0:1] offset:2048
	global_store_dwordx4 v24, v[128:131], s[0:1] offset:3072
	s_nop 1
	v_add_f32_dpp v184, v184, v184 quad_perm:[1,0,3,2] row_mask:0xf bank_mask:0xf
	v_add_f32_dpp v185, v185, v185 quad_perm:[1,0,3,2] row_mask:0xf bank_mask:0xf
	v_add_f32_dpp v186, v186, v186 quad_perm:[1,0,3,2] row_mask:0xf bank_mask:0xf
	v_add_f32_dpp v187, v187, v187 quad_perm:[1,0,3,2] row_mask:0xf bank_mask:0xf
	v_add_f32_dpp v184, v184, v184 quad_perm:[2,3,0,1] row_mask:0xf bank_mask:0xf
	v_add_f32_dpp v185, v185, v185 quad_perm:[2,3,0,1] row_mask:0xf bank_mask:0xf
	v_add_f32_dpp v186, v186, v186 quad_perm:[2,3,0,1] row_mask:0xf bank_mask:0xf
	v_add_f32_dpp v187, v187, v187 quad_perm:[2,3,0,1] row_mask:0xf bank_mask:0xf
	v_add_f32_dpp v184, v184, v184 row_half_mirror row_mask:0xf bank_mask:0xf
	v_add_f32_dpp v185, v185, v185 row_half_mirror row_mask:0xf bank_mask:0xf
	v_add_f32_dpp v186, v186, v186 row_half_mirror row_mask:0xf bank_mask:0xf
	v_add_f32_dpp v187, v187, v187 row_half_mirror row_mask:0xf bank_mask:0xf
	v_add_f32_dpp v184, v184, v184 row_mirror row_mask:0xf bank_mask:0xf
	v_add_f32_dpp v185, v185, v185 row_mirror row_mask:0xf bank_mask:0xf
	v_add_f32_dpp v186, v186, v186 row_mirror row_mask:0xf bank_mask:0xf
	v_add_f32_dpp v187, v187, v187 row_mirror row_mask:0xf bank_mask:0xf
	v_add_f32_dpp v184, v184, v184 row_bcast:15 row_mask:0xa bank_mask:0xf
	v_add_f32_dpp v185, v185, v185 row_bcast:15 row_mask:0xa bank_mask:0xf
	v_add_f32_dpp v186, v186, v186 row_bcast:15 row_mask:0xa bank_mask:0xf
	v_add_f32_dpp v187, v187, v187 row_bcast:15 row_mask:0xa bank_mask:0xf
	v_add_f32_dpp v184, v184, v184 row_bcast:31 row_mask:0xc bank_mask:0xf
	v_add_f32_dpp v185, v185, v185 row_bcast:31 row_mask:0xc bank_mask:0xf
	v_add_f32_dpp v186, v186, v186 row_bcast:31 row_mask:0xc bank_mask:0xf
	v_add_f32_dpp v187, v187, v187 row_bcast:31 row_mask:0xc bank_mask:0xf
	s_nop 1
	v_readlane_b32 s3, v184, 63
	v_readlane_b32 s24, v185, 63
	v_readlane_b32 s98, v186, 63
	v_readlane_b32 s101, v187, 63
	s_nop 3
	v_writelane_b32 v188, s3, 0
	v_writelane_b32 v188, s24, 1
	v_writelane_b32 v188, s98, 2
	v_writelane_b32 v188, s101, 3
	s_nop 1
	v_mul_f32_e32 v188, 0x3a800000, v188
	v_add_f32_e32 v188, 0x358637bd, v188
	v_rsq_f32_e32 v188, v188
	s_mov_b64 exec, 15
	global_store_dword v26, v188, s[14:15]
	s_mov_b64 exec, -1
.LBB0_989:
	s_cmp_gt_i32 s31, 9
	s_cselect_b64 s[0:1], -1, 0
	s_and_b64 s[4:5], s[8:9], s[0:1]
	s_andn2_b64 vcc, exec, s[4:5]
	s_cbranch_vccnz .LBB0_1039
	s_waitcnt vmcnt(0)
	s_barrier
	v_cmp_eq_u32_e32 vcc, 0, v195
	s_and_saveexec_b64 s[4:5], vcc
	s_cbranch_execz .Ltb1039_done
	s_and_b32 s3, s2, 7
	s_lshl_b32 s3, s3, 3
	s_bfe_u32 s13, s2, 0x30003
	s_or_b32 s3, s3, s13
	s_lshl_b32 s3, s3, 5
	s_add_u32 s8, s28, 0x3903600
	s_addc_u32 s9, s29, 0
	v_mov_b32_e32 v0, s3
	v_mov_b32_e32 v1, 1
	v_mov_b32_e32 v2, 28
	s_mov_b32 s15, 0
	s_cmp_eq_u32 s99, 1
	s_cbranch_scc1 .Ltb1039_fast
	buffer_wbl2 sc1
	s_waitcnt vmcnt(0)
	global_atomic_add v0, v1, s[8:9]

; __device__ __forceinline__ unsigned xb_add(unsigned* p, unsigned v) { return __hip_atomic_fetch_add(p, v, __ATOMIC_RELAXED, __HIP_MEMORY_SCOPE_AGENT); }
; #define SEAM(k) do { if (IN(k) && IN((k) + 1)) { xcd_barrier(xbar); } } while (0)
; __device__ __forceinline__ void xcd_barrier(const XcdBarrier& b) {
;     asm volatile("s_waitcnt vmcnt(0)" ::: "memory");
;     __syncthreads();
;     if (threadIdx.x == 0) {
;         unsigned* bar = b.bar;
;         __builtin_amdgcn_s_waitcnt(0);
;         unsigned nloc = b.st[0], nx = b.st[1];
;         if (nloc == 0u) { xcd_barrier_complete(bar, b.x, nloc, nx); b.st[0] = nloc; b.st[1] = nx; }
;         const unsigned old = xb_add(&bar[XB_XSUB(b.x)], 1u);
;         const unsigned gen = old / nloc;
;         if (old + 1u == (gen + 1u) * nloc) {
;             __builtin_amdgcn_fence(__ATOMIC_RELEASE, "agent");
;             asm volatile("s_waitcnt vmcnt(0)" ::: "memory");
;             const unsigned og = xb_add(&bar[XB_TOP], 1u);
; __global__ void __launch_bounds__(NWAVES * 64, 2) mk_fwd(Args a) {
;     ...
;     SEAM(9);
.LBB0_1084:
	s_cmp_gt_i32 s31, 10
	s_cselect_b64 s[0:1], -1, 0
	s_and_b64 s[4:5], s[6:7], s[0:1]
	s_andn2_b64 vcc, exec, s[4:5]
	s_cbranch_vccnz .LBB0_1134
	s_waitcnt vmcnt(0)
	s_barrier
	v_cmp_eq_u32_e32 vcc, 0, v195
	s_and_saveexec_b64 s[4:5], vcc
	s_cbranch_execz .Ltb1134_done
	s_and_b32 s3, s2, 7
	s_lshl_b32 s3, s3, 3
	s_bfe_u32 s13, s2, 0x30003
	s_or_b32 s3, s3, s13
	s_lshl_b32 s3, s3, 5
	s_add_u32 s8, s28, 0x3903600
	s_addc_u32 s9, s29, 0
	v_mov_b32_e32 v0, s3
	v_mov_b32_e32 v1, 1
	v_mov_b32_e32 v2, 32
	s_mov_b32 s15, 0
	s_cmp_eq_u32 s99, 1
	s_cbranch_scc1 .Ltb1134_fast
	buffer_wbl2 sc1
	s_waitcnt vmcnt(0)
	global_atomic_add v0, v1, s[8:9]

; __device__ __forceinline__ unsigned xb_add(unsigned* p, unsigned v) { return __hip_atomic_fetch_add(p, v, __ATOMIC_RELAXED, __HIP_MEMORY_SCOPE_AGENT); }
; #define SEAM(k) do { if (IN(k) && IN((k) + 1)) { xcd_barrier(xbar); } } while (0)
; __device__ __forceinline__ void xcd_barrier(const XcdBarrier& b) {
;     asm volatile("s_waitcnt vmcnt(0)" ::: "memory");
;     __syncthreads();
;     if (threadIdx.x == 0) {
;         unsigned* bar = b.bar;
;         __builtin_amdgcn_s_waitcnt(0);
;         unsigned nloc = b.st[0], nx = b.st[1];
;         if (nloc == 0u) { xcd_barrier_complete(bar, b.x, nloc, nx); b.st[0] = nloc; b.st[1] = nx; }
;         const unsigned old = xb_add(&bar[XB_XSUB(b.x)], 1u);
;         const unsigned gen = old / nloc;
;         if (old + 1u == (gen + 1u) * nloc) {
;             __builtin_amdgcn_fence(__ATOMIC_RELEASE, "agent");
;             asm volatile("s_waitcnt vmcnt(0)" ::: "memory");
;             const unsigned og = xb_add(&bar[XB_TOP], 1u);
; __global__ void __launch_bounds__(NWAVES * 64, 2) mk_fwd(Args a) {
;     ...
;     SEAM(10);
.LBB0_1163:
	s_cmp_gt_i32 s31, 11
	s_cselect_b64 s[0:1], -1, 0
	s_and_b64 s[4:5], s[6:7], s[0:1]
	s_andn2_b64 vcc, exec, s[4:5]
	s_cbranch_vccnz .LBB0_1213
	s_waitcnt vmcnt(0)
	s_barrier
	v_cmp_eq_u32_e32 vcc, 0, v195
	s_and_saveexec_b64 s[4:5], vcc
	s_cbranch_execz .Ltb1213_done
	s_and_b32 s3, s2, 7
	s_lshl_b32 s3, s3, 3
	s_bfe_u32 s13, s2, 0x30003
	s_or_b32 s3, s3, s13
	s_lshl_b32 s3, s3, 5
	s_add_u32 s8, s28, 0x3903600
	s_addc_u32 s9, s29, 0
	v_mov_b32_e32 v0, s3
	v_mov_b32_e32 v1, 1
	v_mov_b32_e32 v2, 36
	s_mov_b32 s15, 0
	s_cmp_eq_u32 s99, 1
	s_cbranch_scc1 .Ltb1213_fast
	buffer_wbl2 sc1
	s_waitcnt vmcnt(0)
	global_atomic_add v0, v1, s[8:9]

; __device__ __forceinline__ unsigned xb_add(unsigned* p, unsigned v) { return __hip_atomic_fetch_add(p, v, __ATOMIC_RELAXED, __HIP_MEMORY_SCOPE_AGENT); }
; #define SEAM(k) do { if (IN(k) && IN((k) + 1)) { xcd_barrier(xbar); } } while (0)
; __device__ __forceinline__ void xcd_barrier(const XcdBarrier& b) {
;     asm volatile("s_waitcnt vmcnt(0)" ::: "memory");
;     __syncthreads();
;     if (threadIdx.x == 0) {
;         unsigned* bar = b.bar;
;         __builtin_amdgcn_s_waitcnt(0);
;         unsigned nloc = b.st[0], nx = b.st[1];
;         if (nloc == 0u) { xcd_barrier_complete(bar, b.x, nloc, nx); b.st[0] = nloc; b.st[1] = nx; }
;         const unsigned old = xb_add(&bar[XB_XSUB(b.x)], 1u);
;         const unsigned gen = old / nloc;
;         if (old + 1u == (gen + 1u) * nloc) {
;             __builtin_amdgcn_fence(__ATOMIC_RELEASE, "agent");
;             asm volatile("s_waitcnt vmcnt(0)" ::: "memory");
;             const unsigned og = xb_add(&bar[XB_TOP], 1u);
; __global__ void __launch_bounds__(NWAVES * 64, 2) mk_fwd(Args a) {
;     ...
;     SEAM(11);
.LBB0_1259:
	s_cmp_gt_i32 s31, 12
	s_cselect_b64 s[0:1], -1, 0
	s_and_b64 s[4:5], s[8:9], s[0:1]
	s_andn2_b64 vcc, exec, s[4:5]
	s_cbranch_vccnz .LBB0_1309
	s_waitcnt vmcnt(0)
	s_barrier
	v_cmp_eq_u32_e32 vcc, 0, v195
	s_and_saveexec_b64 s[4:5], vcc
	s_cbranch_execz .Ltb1309_done
	s_and_b32 s3, s2, 7
	s_lshl_b32 s3, s3, 3
	s_bfe_u32 s13, s2, 0x30003
	s_or_b32 s3, s3, s13
	s_lshl_b32 s3, s3, 5
	s_add_u32 s8, s28, 0x3903600
	s_addc_u32 s9, s29, 0
	v_mov_b32_e32 v0, s3
	v_mov_b32_e32 v1, 1
	v_mov_b32_e32 v2, 40
	s_mov_b32 s15, 0
	s_cmp_eq_u32 s99, 1
	s_cbranch_scc1 .Ltb1309_fast
	buffer_wbl2 sc1
	s_waitcnt vmcnt(0)
	global_atomic_add v0, v1, s[8:9]

; __device__ __forceinline__ unsigned xb_add(unsigned* p, unsigned v) { return __hip_atomic_fetch_add(p, v, __ATOMIC_RELAXED, __HIP_MEMORY_SCOPE_AGENT); }
; #define SEAM(k) do { if (IN(k) && IN((k) + 1)) { xcd_barrier(xbar); } } while (0)
; __device__ __forceinline__ void xcd_barrier(const XcdBarrier& b) {
;     asm volatile("s_waitcnt vmcnt(0)" ::: "memory");
;     __syncthreads();
;     if (threadIdx.x == 0) {
;         unsigned* bar = b.bar;
;         __builtin_amdgcn_s_waitcnt(0);
;         unsigned nloc = b.st[0], nx = b.st[1];
;         if (nloc == 0u) { xcd_barrier_complete(bar, b.x, nloc, nx); b.st[0] = nloc; b.st[1] = nx; }
;         const unsigned old = xb_add(&bar[XB_XSUB(b.x)], 1u);
;         const unsigned gen = old / nloc;
;         if (old + 1u == (gen + 1u) * nloc) {
;             __builtin_amdgcn_fence(__ATOMIC_RELEASE, "agent");
;             asm volatile("s_waitcnt vmcnt(0)" ::: "memory");
;             const unsigned og = xb_add(&bar[XB_TOP], 1u);
; __global__ void __launch_bounds__(NWAVES * 64, 2) mk_fwd(Args a) {
;     ...
;     SEAM(13);
.LBB0_1396:
	s_cmp_gt_i32 s31, 14
	s_cselect_b64 s[0:1], -1, 0
	s_and_b64 s[4:5], s[8:9], s[0:1]
	s_andn2_b64 vcc, exec, s[4:5]
	s_cbranch_vccnz .LBB0_1446
	s_waitcnt vmcnt(0)
	s_barrier
	v_cmp_eq_u32_e32 vcc, 0, v195
	s_and_saveexec_b64 s[4:5], vcc
	s_cbranch_execz .Ltb1446_done
	s_and_b32 s3, s2, 7
	s_lshl_b32 s3, s3, 3
	s_bfe_u32 s13, s2, 0x30003
	s_or_b32 s3, s3, s13
	s_lshl_b32 s3, s3, 5
	s_add_u32 s8, s28, 0x3903600
	s_addc_u32 s9, s29, 0
	v_mov_b32_e32 v0, s3
	v_mov_b32_e32 v1, 1
	v_mov_b32_e32 v2, 44
	s_mov_b32 s15, 0
	s_cmp_eq_u32 s99, 1
	s_cbranch_scc1 .Ltb1446_fast
	buffer_wbl2 sc1
	s_waitcnt vmcnt(0)
	global_atomic_add v0, v1, s[8:9]
